# statpf + move both ret_kv tiles from compress blocks to blocks 256..511 (mixer rebalance)
# baseline (speedup 1.0000x reference)
.LBB0_621:
	s_add_u32 s0, s0, 0x80
	s_addc_u32 s1, s1, 0
	s_waitcnt vmcnt(0)
	v_mov_b32_e32 v2, v176
	v_mov_b32_e32 v3, v177
	v_mov_b32_e32 v4, v178
	v_mov_b32_e32 v5, v179
	v_mov_b32_e32 v6, v180
	v_mov_b32_e32 v7, v181
	v_mov_b32_e32 v8, v182
	v_mov_b32_e32 v9, v183
	v_mov_b32_e32 v20, v184
	v_mov_b32_e32 v21, v185
	v_mov_b32_e32 v22, v186
	v_mov_b32_e32 v23, v187
	v_mov_b32_e32 v24, v188
	v_mov_b32_e32 v25, v189
	v_mov_b32_e32 v26, v190
	v_mov_b32_e32 v27, v191
	global_load_dwordx4 v[176:179], v[172:173], off offset:1136
	global_load_dwordx4 v[180:183], v[172:173], off offset:1120
	global_load_dwordx4 v[184:187], v[172:173], off offset:1104
	global_load_dwordx4 v[188:191], v[172:173], off offset:1088
	s_cmp_lg_u32 s0, s65
	v_lshlrev_b32_e32 v0, 16, v24
	v_mul_f32_e32 v19, v0, v0
	v_fmamk_f32 v19, v19, 0xbdd2d3e7, v129
	v_mul_f32_e32 v19, v19, v0
	v_exp_f32_e32 v19, v19
	v_and_b32_e32 v40, 0xffff0000, v27
	v_add_f32_e32 v19, 1.0, v19
	v_rcp_f32_e32 v19, v19
	s_nop 0
	v_mul_f32_e32 v29, v19, v0
	v_and_b32_e32 v0, 0xffff0000, v24
	v_mul_f32_e32 v19, v0, v0
	v_fmamk_f32 v19, v19, 0xbdd2d3e7, v129
	v_mul_f32_e32 v19, v19, v0
	v_exp_f32_e32 v19, v19
	v_mul_f32_e32 v28, v29, v29
	v_add_f32_e32 v19, 1.0, v19
	v_rcp_f32_e32 v19, v19
	s_nop 0
	v_mul_f32_e32 v33, v19, v0
	v_lshlrev_b32_e32 v0, 16, v25
	v_mul_f32_e32 v19, v0, v0
	v_fmamk_f32 v19, v19, 0xbdd2d3e7, v129
	v_mul_f32_e32 v19, v19, v0
	v_exp_f32_e32 v19, v19
	v_mul_f32_e32 v32, v33, v33
	v_add_f32_e32 v19, 1.0, v19
	v_rcp_f32_e32 v19, v19
	s_nop 0
	v_mul_f32_e32 v35, v19, v0
	v_and_b32_e32 v0, 0xffff0000, v25
	v_mul_f32_e32 v19, v0, v0
	v_fmamk_f32 v19, v19, 0xbdd2d3e7, v129
	v_mul_f32_e32 v19, v19, v0
	v_exp_f32_e32 v19, v19
	v_mul_f32_e32 v34, v35, v35
	v_add_f32_e32 v19, 1.0, v19
	v_rcp_f32_e32 v19, v19
	s_nop 0
	v_mul_f32_e32 v25, v19, v0
	v_lshlrev_b32_e32 v0, 16, v26
	v_mul_f32_e32 v19, v0, v0
	v_fmamk_f32 v19, v19, 0xbdd2d3e7, v129
	v_mul_f32_e32 v19, v19, v0
	v_exp_f32_e32 v19, v19
	v_mul_f32_e32 v24, v25, v25
	v_pk_add_f32 v[24:25], v[34:35], v[24:25]
	v_add_f32_e32 v19, 1.0, v19
	v_rcp_f32_e32 v19, v19
	s_nop 0
	v_mul_f32_e32 v37, v19, v0
	v_and_b32_e32 v0, 0xffff0000, v26
	v_mul_f32_e32 v19, v0, v0
	v_fmamk_f32 v19, v19, 0xbdd2d3e7, v129
	v_mul_f32_e32 v19, v19, v0
	v_exp_f32_e32 v19, v19
	v_mul_f32_e32 v26, v40, v40
	v_fmamk_f32 v26, v26, 0xbdd2d3e7, v129
	v_mul_f32_e32 v26, v26, v40
	v_add_f32_e32 v19, 1.0, v19
	v_rcp_f32_e32 v19, v19
	v_exp_f32_e32 v26, v26
	v_mul_f32_e32 v39, v19, v0
	v_lshlrev_b32_e32 v0, 16, v27
	v_mul_f32_e32 v19, v0, v0
	v_fmamk_f32 v19, v19, 0xbdd2d3e7, v129
	v_mul_f32_e32 v19, v19, v0
	v_exp_f32_e32 v19, v19
	v_add_f32_e32 v26, 1.0, v26
	v_rcp_f32_e32 v41, v26
	v_pk_add_f32 v[26:27], v[28:29], v[32:33]
	v_add_f32_e32 v19, 1.0, v19
	v_rcp_f32_e32 v19, v19
	v_mul_f32_e32 v36, v37, v37
	v_mul_f32_e32 v38, v39, v39
	v_pk_add_f32 v[14:15], v[14:15], v[26:27]
	v_mul_f32_e32 v27, v41, v40
	v_pk_add_f32 v[14:15], v[14:15], v[24:25]
	v_pk_add_f32 v[24:25], v[36:37], v[38:39]
	v_mul_f32_e32 v26, v27, v27
	v_pk_add_f32 v[14:15], v[14:15], v[24:25]
	v_mul_f32_e32 v25, v19, v0
	v_lshlrev_b32_e32 v0, 16, v20
	v_mul_f32_e32 v19, v0, v0
	v_fmamk_f32 v19, v19, 0xbdd2d3e7, v129
	v_mul_f32_e32 v19, v19, v0
	v_exp_f32_e32 v19, v19
	v_mul_f32_e32 v24, v25, v25
	v_pk_add_f32 v[24:25], v[24:25], v[26:27]
	v_and_b32_e32 v36, 0xffff0000, v23
	v_add_f32_e32 v19, 1.0, v19
	v_rcp_f32_e32 v19, v19
	v_pk_add_f32 v[14:15], v[14:15], v[24:25]
	v_mul_f32_e32 v25, v19, v0
	v_and_b32_e32 v0, 0xffff0000, v20
	v_mul_f32_e32 v19, v0, v0
	v_fmamk_f32 v19, v19, 0xbdd2d3e7, v129
	v_mul_f32_e32 v19, v19, v0
	v_exp_f32_e32 v19, v19
	v_mul_f32_e32 v24, v25, v25
	v_add_f32_e32 v19, 1.0, v19
	v_rcp_f32_e32 v19, v19
	s_nop 0
	v_mul_f32_e32 v27, v19, v0
	v_lshlrev_b32_e32 v0, 16, v21
	v_mul_f32_e32 v19, v0, v0
	v_fmamk_f32 v19, v19, 0xbdd2d3e7, v129
	v_mul_f32_e32 v19, v19, v0
	v_exp_f32_e32 v19, v19
	v_mul_f32_e32 v26, v27, v27
	v_add_f32_e32 v19, 1.0, v19
	v_rcp_f32_e32 v19, v19
	s_nop 0
	v_mul_f32_e32 v29, v19, v0
	v_and_b32_e32 v0, 0xffff0000, v21
	v_mul_f32_e32 v19, v0, v0
	v_fmamk_f32 v19, v19, 0xbdd2d3e7, v129
	v_mul_f32_e32 v19, v19, v0
	v_exp_f32_e32 v19, v19
	v_mul_f32_e32 v28, v29, v29
	v_add_f32_e32 v19, 1.0, v19
	v_rcp_f32_e32 v19, v19
	s_nop 0
	v_mul_f32_e32 v21, v19, v0
	v_lshlrev_b32_e32 v0, 16, v22
	v_mul_f32_e32 v19, v0, v0
	v_fmamk_f32 v19, v19, 0xbdd2d3e7, v129
	v_mul_f32_e32 v19, v19, v0
	v_exp_f32_e32 v19, v19
	v_mul_f32_e32 v20, v21, v21
	v_pk_add_f32 v[20:21], v[28:29], v[20:21]
	v_add_f32_e32 v19, 1.0, v19
	v_rcp_f32_e32 v19, v19
	s_nop 0
	v_mul_f32_e32 v33, v19, v0
	v_and_b32_e32 v0, 0xffff0000, v22
	v_mul_f32_e32 v19, v0, v0
	v_fmamk_f32 v19, v19, 0xbdd2d3e7, v129
	v_mul_f32_e32 v19, v19, v0
	v_exp_f32_e32 v19, v19
	v_mul_f32_e32 v22, v36, v36
	v_fmamk_f32 v22, v22, 0xbdd2d3e7, v129
	v_mul_f32_e32 v22, v22, v36
	v_add_f32_e32 v19, 1.0, v19
	v_rcp_f32_e32 v19, v19
	v_exp_f32_e32 v22, v22
	v_mul_f32_e32 v35, v19, v0
	v_lshlrev_b32_e32 v0, 16, v23
	v_mul_f32_e32 v19, v0, v0
	v_fmamk_f32 v19, v19, 0xbdd2d3e7, v129
	v_mul_f32_e32 v19, v19, v0
	v_exp_f32_e32 v19, v19
	v_add_f32_e32 v22, 1.0, v22
	v_rcp_f32_e32 v37, v22
	v_pk_add_f32 v[22:23], v[24:25], v[26:27]
	v_add_f32_e32 v19, 1.0, v19
	v_rcp_f32_e32 v19, v19
	v_mul_f32_e32 v32, v33, v33
	v_mul_f32_e32 v34, v35, v35
	v_pk_add_f32 v[14:15], v[14:15], v[22:23]
	v_mul_f32_e32 v23, v37, v36
	v_pk_add_f32 v[14:15], v[14:15], v[20:21]
	v_pk_add_f32 v[20:21], v[32:33], v[34:35]
	v_mul_f32_e32 v22, v23, v23
	v_pk_add_f32 v[14:15], v[14:15], v[20:21]
	v_mul_f32_e32 v21, v19, v0
	v_lshlrev_b32_e32 v0, 16, v6
	v_mul_f32_e32 v19, v0, v0
	v_fmamk_f32 v19, v19, 0xbdd2d3e7, v129
	v_mul_f32_e32 v19, v19, v0
	v_exp_f32_e32 v19, v19
	v_mul_f32_e32 v20, v21, v21
	v_pk_add_f32 v[20:21], v[20:21], v[22:23]
	v_and_b32_e32 v32, 0xffff0000, v9
	v_add_f32_e32 v19, 1.0, v19
	v_rcp_f32_e32 v19, v19
	v_pk_add_f32 v[14:15], v[14:15], v[20:21]
	v_mul_f32_e32 v21, v19, v0
	v_and_b32_e32 v0, 0xffff0000, v6
	v_mul_f32_e32 v6, v0, v0
	v_fmamk_f32 v6, v6, 0xbdd2d3e7, v129
	v_mul_f32_e32 v6, v6, v0
	v_exp_f32_e32 v6, v6
	v_mul_f32_e32 v20, v21, v21
	v_add_f32_e32 v6, 1.0, v6
	v_rcp_f32_e32 v6, v6
	s_nop 0
	v_mul_f32_e32 v23, v6, v0
	v_lshlrev_b32_e32 v0, 16, v7
	v_mul_f32_e32 v6, v0, v0
	v_fmamk_f32 v6, v6, 0xbdd2d3e7, v129
	v_mul_f32_e32 v6, v6, v0
	v_exp_f32_e32 v6, v6
	v_mul_f32_e32 v22, v23, v23
	v_add_f32_e32 v6, 1.0, v6
	v_rcp_f32_e32 v6, v6
	s_nop 0
	v_mul_f32_e32 v25, v6, v0
	v_and_b32_e32 v0, 0xffff0000, v7
	v_mul_f32_e32 v6, v0, v0
	v_fmamk_f32 v6, v6, 0xbdd2d3e7, v129
	v_mul_f32_e32 v6, v6, v0
	v_exp_f32_e32 v6, v6
	v_mul_f32_e32 v24, v25, v25
	v_add_f32_e32 v6, 1.0, v6
	v_rcp_f32_e32 v6, v6
	s_nop 0
	v_mul_f32_e32 v7, v6, v0
	v_lshlrev_b32_e32 v0, 16, v8
	v_mul_f32_e32 v19, v0, v0
	v_fmamk_f32 v19, v19, 0xbdd2d3e7, v129
	v_mul_f32_e32 v19, v19, v0
	v_exp_f32_e32 v19, v19
	v_mul_f32_e32 v6, v7, v7
	v_pk_add_f32 v[6:7], v[24:25], v[6:7]
	v_add_f32_e32 v19, 1.0, v19
	v_rcp_f32_e32 v19, v19
	s_nop 0
	v_mul_f32_e32 v27, v19, v0
	v_and_b32_e32 v0, 0xffff0000, v8
	v_mul_f32_e32 v8, v0, v0
	v_fmamk_f32 v8, v8, 0xbdd2d3e7, v129
	v_mul_f32_e32 v8, v8, v0
	v_exp_f32_e32 v8, v8
	v_mul_f32_e32 v26, v27, v27
	v_add_f32_e32 v8, 1.0, v8
	v_rcp_f32_e32 v8, v8
	s_nop 0
	v_mul_f32_e32 v29, v8, v0
	v_lshlrev_b32_e32 v0, 16, v9
	v_mul_f32_e32 v8, v0, v0
	v_fmamk_f32 v8, v8, 0xbdd2d3e7, v129
	v_mul_f32_e32 v8, v8, v0
	v_exp_f32_e32 v8, v8
	v_mul_f32_e32 v28, v29, v29
	v_add_f32_e32 v8, 1.0, v8
	v_rcp_f32_e32 v19, v8
	v_mul_f32_e32 v8, v32, v32
	v_fmamk_f32 v8, v8, 0xbdd2d3e7, v129
	v_mul_f32_e32 v8, v8, v32
	v_exp_f32_e32 v8, v8
	s_nop 0
	v_add_f32_e32 v8, 1.0, v8
	v_rcp_f32_e32 v33, v8
	v_pk_add_f32 v[8:9], v[20:21], v[22:23]
	s_nop 0
	v_pk_add_f32 v[8:9], v[14:15], v[8:9]
	v_mul_f32_e32 v15, v33, v32
	v_pk_add_f32 v[6:7], v[8:9], v[6:7]
	v_pk_add_f32 v[8:9], v[26:27], v[28:29]
	v_mul_f32_e32 v14, v15, v15
	v_pk_add_f32 v[6:7], v[6:7], v[8:9]
	v_mul_f32_e32 v9, v19, v0
	v_mul_f32_e32 v8, v9, v9
	v_pk_add_f32 v[8:9], v[8:9], v[14:15]
	v_lshlrev_b32_e32 v0, 16, v2
	v_pk_add_f32 v[6:7], v[6:7], v[8:9]
	v_mul_f32_e32 v8, v0, v0
	v_fmamk_f32 v8, v8, 0xbdd2d3e7, v129
	v_mul_f32_e32 v8, v8, v0
	v_exp_f32_e32 v8, v8
	v_and_b32_e32 v26, 0xffff0000, v5
	v_add_f32_e32 v8, 1.0, v8
	v_rcp_f32_e32 v8, v8
	s_nop 0
	v_mul_f32_e32 v9, v8, v0
	v_and_b32_e32 v0, 0xffff0000, v2
	v_mul_f32_e32 v2, v0, v0
	v_fmamk_f32 v2, v2, 0xbdd2d3e7, v129
	v_mul_f32_e32 v2, v2, v0
	v_exp_f32_e32 v2, v2
	v_mul_f32_e32 v8, v9, v9
	v_add_f32_e32 v2, 1.0, v2
	v_rcp_f32_e32 v2, v2
	s_nop 0
	v_mul_f32_e32 v15, v2, v0
	v_lshlrev_b32_e32 v0, 16, v3
	v_mul_f32_e32 v2, v0, v0
	v_fmamk_f32 v2, v2, 0xbdd2d3e7, v129
	v_mul_f32_e32 v2, v2, v0
	v_exp_f32_e32 v2, v2
	v_mul_f32_e32 v14, v15, v15
	v_add_f32_e32 v2, 1.0, v2
	v_rcp_f32_e32 v2, v2
	s_nop 0
	v_mul_f32_e32 v21, v2, v0
	v_and_b32_e32 v0, 0xffff0000, v3
	v_mul_f32_e32 v2, v0, v0
	v_fmamk_f32 v2, v2, 0xbdd2d3e7, v129
	v_mul_f32_e32 v2, v2, v0
	v_exp_f32_e32 v2, v2
	v_mul_f32_e32 v20, v21, v21
	v_add_f32_e32 v2, 1.0, v2
	v_rcp_f32_e32 v2, v2
	s_nop 0
	v_mul_f32_e32 v3, v2, v0
	v_lshlrev_b32_e32 v0, 16, v4
	v_mul_f32_e32 v19, v0, v0
	v_fmamk_f32 v19, v19, 0xbdd2d3e7, v129
	v_mul_f32_e32 v19, v19, v0
	v_exp_f32_e32 v19, v19
	v_mul_f32_e32 v2, v3, v3
	v_pk_add_f32 v[2:3], v[20:21], v[2:3]
	v_add_f32_e32 v19, 1.0, v19
	v_rcp_f32_e32 v19, v19
	s_nop 0
	v_mul_f32_e32 v23, v19, v0
	v_and_b32_e32 v0, 0xffff0000, v4
	v_mul_f32_e32 v4, v0, v0
	v_fmamk_f32 v4, v4, 0xbdd2d3e7, v129
	v_mul_f32_e32 v4, v4, v0
	v_exp_f32_e32 v4, v4
	v_mul_f32_e32 v22, v23, v23
	v_add_f32_e32 v4, 1.0, v4
	v_rcp_f32_e32 v4, v4
	s_nop 0
	v_mul_f32_e32 v25, v4, v0
	v_lshlrev_b32_e32 v0, 16, v5
	v_mul_f32_e32 v4, v0, v0
	v_fmamk_f32 v4, v4, 0xbdd2d3e7, v129
	v_mul_f32_e32 v4, v4, v0
	v_exp_f32_e32 v4, v4
	v_mul_f32_e32 v24, v25, v25
	v_add_f32_e32 v4, 1.0, v4
	v_rcp_f32_e32 v19, v4
	v_mul_f32_e32 v4, v26, v26
	v_fmamk_f32 v4, v4, 0xbdd2d3e7, v129
	v_mul_f32_e32 v4, v4, v26
	v_exp_f32_e32 v4, v4
	s_nop 0
	v_add_f32_e32 v4, 1.0, v4
	v_rcp_f32_e32 v27, v4
	v_pk_add_f32 v[4:5], v[8:9], v[14:15]
	s_nop 0
	v_pk_add_f32 v[4:5], v[6:7], v[4:5]
	v_mul_f32_e32 v7, v27, v26
	v_pk_add_f32 v[2:3], v[4:5], v[2:3]
	v_pk_add_f32 v[4:5], v[22:23], v[24:25]
	v_mul_f32_e32 v6, v7, v7
	v_pk_add_f32 v[2:3], v[2:3], v[4:5]
	v_mul_f32_e32 v5, v19, v0
	v_mul_f32_e32 v4, v5, v5
	v_pk_add_f32 v[4:5], v[4:5], v[6:7]
	s_nop 0
	v_pk_add_f32 v[24:25], v[2:3], v[4:5]
	s_waitcnt vmcnt(0)
	v_mov_b32_e32 v2, v176
	v_mov_b32_e32 v3, v177
	v_mov_b32_e32 v4, v178
	v_mov_b32_e32 v5, v179
	v_mov_b32_e32 v6, v180
	v_mov_b32_e32 v7, v181
	v_mov_b32_e32 v8, v182
	v_mov_b32_e32 v9, v183
	v_mov_b32_e32 v20, v184
	v_mov_b32_e32 v21, v185
	v_mov_b32_e32 v22, v186
	v_mov_b32_e32 v23, v187
	v_mov_b32_e32 v14, v188
	v_mov_b32_e32 v15, v189
	v_mov_b32_e32 v16, v190
	v_mov_b32_e32 v17, v191
	v_lshl_add_u64 v[172:173], v[12:13], 0, s[0:1]
	global_load_dwordx4 v[176:179], v[172:173], off offset:1072
	global_load_dwordx4 v[180:183], v[172:173], off offset:1056
	global_load_dwordx4 v[184:187], v[172:173], off offset:1040
	global_load_dwordx4 v[188:191], v[172:173], off offset:1024
	v_lshlrev_b32_e32 v0, 16, v14
	v_mul_f32_e32 v19, v0, v0
	v_fmamk_f32 v19, v19, 0xbdd2d3e7, v129
	v_mul_f32_e32 v19, v19, v0
	v_exp_f32_e32 v19, v19
	v_and_b32_e32 v38, 0xffff0000, v17
	v_add_f32_e32 v19, 1.0, v19
	v_rcp_f32_e32 v19, v19
	s_nop 0
	v_mul_f32_e32 v27, v19, v0
	v_and_b32_e32 v0, 0xffff0000, v14
	v_mul_f32_e32 v14, v0, v0
	v_fmamk_f32 v14, v14, 0xbdd2d3e7, v129
	v_mul_f32_e32 v14, v14, v0
	v_exp_f32_e32 v14, v14
	v_mul_f32_e32 v26, v27, v27
	v_add_f32_e32 v14, 1.0, v14
	v_rcp_f32_e32 v14, v14
	s_nop 0
	v_mul_f32_e32 v29, v14, v0
	v_lshlrev_b32_e32 v0, 16, v15
	v_mul_f32_e32 v14, v0, v0
	v_fmamk_f32 v14, v14, 0xbdd2d3e7, v129
	v_mul_f32_e32 v14, v14, v0
	v_exp_f32_e32 v14, v14
	v_mul_f32_e32 v28, v29, v29
	v_add_f32_e32 v14, 1.0, v14
	v_rcp_f32_e32 v14, v14
	s_nop 0
	v_mul_f32_e32 v33, v14, v0
	v_and_b32_e32 v0, 0xffff0000, v15
	v_mul_f32_e32 v14, v0, v0
	v_fmamk_f32 v14, v14, 0xbdd2d3e7, v129
	v_mul_f32_e32 v14, v14, v0
	v_exp_f32_e32 v14, v14
	v_mul_f32_e32 v32, v33, v33
	v_add_f32_e32 v14, 1.0, v14
	v_rcp_f32_e32 v14, v14
	s_nop 0
	v_mul_f32_e32 v15, v14, v0
	v_lshlrev_b32_e32 v0, 16, v16
	v_mul_f32_e32 v19, v0, v0
	v_fmamk_f32 v19, v19, 0xbdd2d3e7, v129
	v_mul_f32_e32 v19, v19, v0
	v_exp_f32_e32 v19, v19
	v_mul_f32_e32 v14, v15, v15
	v_pk_add_f32 v[14:15], v[32:33], v[14:15]
	v_add_f32_e32 v19, 1.0, v19
	v_rcp_f32_e32 v19, v19
	s_nop 0
	v_mul_f32_e32 v35, v19, v0
	v_and_b32_e32 v0, 0xffff0000, v16
	v_mul_f32_e32 v16, v0, v0
	v_fmamk_f32 v16, v16, 0xbdd2d3e7, v129
	v_mul_f32_e32 v16, v16, v0
	v_exp_f32_e32 v16, v16
	v_mul_f32_e32 v34, v35, v35
	v_add_f32_e32 v16, 1.0, v16
	v_rcp_f32_e32 v16, v16
	s_nop 0
	v_mul_f32_e32 v37, v16, v0
	v_lshlrev_b32_e32 v0, 16, v17
	v_mul_f32_e32 v16, v0, v0
	v_fmamk_f32 v16, v16, 0xbdd2d3e7, v129
	v_mul_f32_e32 v16, v16, v0
	v_exp_f32_e32 v16, v16
	v_mul_f32_e32 v36, v37, v37
	v_add_f32_e32 v16, 1.0, v16
	v_rcp_f32_e32 v19, v16
	v_mul_f32_e32 v16, v38, v38
	v_fmamk_f32 v16, v16, 0xbdd2d3e7, v129
	v_mul_f32_e32 v16, v16, v38
	v_exp_f32_e32 v16, v16
	s_nop 0
	v_add_f32_e32 v16, 1.0, v16
	v_rcp_f32_e32 v39, v16
	v_pk_add_f32 v[16:17], v[26:27], v[28:29]
	s_nop 0
	v_pk_add_f32 v[16:17], v[24:25], v[16:17]
	v_mul_f32_e32 v25, v39, v38
	v_pk_add_f32 v[14:15], v[16:17], v[14:15]
	v_pk_add_f32 v[16:17], v[34:35], v[36:37]
	v_mul_f32_e32 v24, v25, v25
	v_pk_add_f32 v[14:15], v[14:15], v[16:17]
	v_mul_f32_e32 v17, v19, v0
	v_mul_f32_e32 v16, v17, v17
	v_pk_add_f32 v[16:17], v[16:17], v[24:25]
	v_lshlrev_b32_e32 v0, 16, v20
	v_pk_add_f32 v[14:15], v[14:15], v[16:17]
	v_mul_f32_e32 v16, v0, v0
	v_fmamk_f32 v16, v16, 0xbdd2d3e7, v129
	v_mul_f32_e32 v16, v16, v0
	v_exp_f32_e32 v16, v16
	s_nop 0
	v_add_f32_e32 v16, 1.0, v16
	v_rcp_f32_e32 v16, v16
	s_nop 0
	v_mul_f32_e32 v17, v16, v0
	v_and_b32_e32 v0, 0xffff0000, v20
	v_mul_f32_e32 v16, v0, v0
	v_fmamk_f32 v16, v16, 0xbdd2d3e7, v129
	v_mul_f32_e32 v16, v16, v0
	v_exp_f32_e32 v16, v16
	s_nop 0
	v_add_f32_e32 v16, 1.0, v16
	v_rcp_f32_e32 v16, v16
	s_nop 0
	v_mul_f32_e32 v25, v16, v0
	v_lshlrev_b32_e32 v0, 16, v21
	v_mul_f32_e32 v19, v0, v0
	v_fmamk_f32 v19, v19, 0xbdd2d3e7, v129
	v_mul_f32_e32 v19, v19, v0
	v_exp_f32_e32 v19, v19
	v_mul_f32_e32 v16, v17, v17
	v_mul_f32_e32 v24, v25, v25
	v_pk_add_f32 v[16:17], v[16:17], v[24:25]
	v_add_f32_e32 v19, 1.0, v19
	v_rcp_f32_e32 v19, v19
	v_pk_add_f32 v[14:15], v[14:15], v[16:17]
	v_mul_f32_e32 v27, v19, v0
	v_and_b32_e32 v0, 0xffff0000, v21
	v_mul_f32_e32 v19, v0, v0
	v_fmamk_f32 v19, v19, 0xbdd2d3e7, v129
	v_mul_f32_e32 v19, v19, v0
	v_exp_f32_e32 v19, v19
	v_mul_f32_e32 v26, v27, v27
	v_add_f32_e32 v19, 1.0, v19
	v_rcp_f32_e32 v19, v19
	s_nop 0
	v_mul_f32_e32 v21, v19, v0
	v_lshlrev_b32_e32 v0, 16, v22
	v_mul_f32_e32 v19, v0, v0
	v_fmamk_f32 v19, v19, 0xbdd2d3e7, v129
	v_mul_f32_e32 v19, v19, v0
	v_exp_f32_e32 v19, v19
	v_mul_f32_e32 v20, v21, v21
	v_pk_add_f32 v[16:17], v[26:27], v[20:21]
	v_add_f32_e32 v19, 1.0, v19
	v_rcp_f32_e32 v19, v19
	v_pk_add_f32 v[14:15], v[14:15], v[16:17]
	v_mul_f32_e32 v29, v19, v0
	v_and_b32_e32 v0, 0xffff0000, v22
	v_mul_f32_e32 v19, v0, v0
	v_fmamk_f32 v19, v19, 0xbdd2d3e7, v129
	v_mul_f32_e32 v19, v19, v0
	v_exp_f32_e32 v19, v19
	v_and_b32_e32 v22, 0xffff0000, v23
	v_mul_f32_e32 v28, v29, v29
	v_add_f32_e32 v19, 1.0, v19
	v_rcp_f32_e32 v19, v19
	s_nop 0
	v_mul_f32_e32 v33, v19, v0
	v_lshlrev_b32_e32 v0, 16, v23
	v_mul_f32_e32 v19, v0, v0
	v_mul_f32_e32 v23, v22, v22
	v_fmamk_f32 v19, v19, 0xbdd2d3e7, v129
	v_fmamk_f32 v23, v23, 0xbdd2d3e7, v129
	v_mul_f32_e32 v19, v19, v0
	v_mul_f32_e32 v23, v23, v22
	v_exp_f32_e32 v19, v19
	v_exp_f32_e32 v23, v23
	v_mul_f32_e32 v32, v33, v33
	v_pk_add_f32 v[16:17], v[28:29], v[32:33]
	v_add_f32_e32 v19, 1.0, v19
	v_add_f32_e32 v23, 1.0, v23
	v_rcp_f32_e32 v19, v19
	v_rcp_f32_e32 v23, v23
	v_pk_add_f32 v[14:15], v[14:15], v[16:17]
	v_and_b32_e32 v28, 0xffff0000, v9
	v_mul_f32_e32 v17, v19, v0
	v_mul_f32_e32 v21, v23, v22
	v_mul_f32_e32 v16, v17, v17
	v_mul_f32_e32 v20, v21, v21
	v_pk_add_f32 v[16:17], v[16:17], v[20:21]
	v_lshlrev_b32_e32 v0, 16, v6
	v_pk_add_f32 v[14:15], v[14:15], v[16:17]
	v_mul_f32_e32 v16, v0, v0
	v_fmamk_f32 v16, v16, 0xbdd2d3e7, v129
	v_mul_f32_e32 v16, v16, v0
	v_exp_f32_e32 v16, v16
	s_nop 0
	v_add_f32_e32 v16, 1.0, v16
	v_rcp_f32_e32 v16, v16
	s_nop 0
	v_mul_f32_e32 v17, v16, v0
	v_and_b32_e32 v0, 0xffff0000, v6
	v_mul_f32_e32 v6, v0, v0
	v_fmamk_f32 v6, v6, 0xbdd2d3e7, v129
	v_mul_f32_e32 v6, v6, v0
	v_exp_f32_e32 v6, v6
	v_mul_f32_e32 v16, v17, v17
	v_add_f32_e32 v6, 1.0, v6
	v_rcp_f32_e32 v6, v6
	s_nop 0
	v_mul_f32_e32 v21, v6, v0
	v_lshlrev_b32_e32 v0, 16, v7
	v_mul_f32_e32 v6, v0, v0
	v_fmamk_f32 v6, v6, 0xbdd2d3e7, v129
	v_mul_f32_e32 v6, v6, v0
	v_exp_f32_e32 v6, v6
	v_mul_f32_e32 v20, v21, v21
	v_add_f32_e32 v6, 1.0, v6
	v_rcp_f32_e32 v6, v6
	s_nop 0
	v_mul_f32_e32 v23, v6, v0
	v_and_b32_e32 v0, 0xffff0000, v7
	v_mul_f32_e32 v6, v0, v0
	v_fmamk_f32 v6, v6, 0xbdd2d3e7, v129
	v_mul_f32_e32 v6, v6, v0
	v_exp_f32_e32 v6, v6
	v_mul_f32_e32 v22, v23, v23
	v_add_f32_e32 v6, 1.0, v6
	v_rcp_f32_e32 v6, v6
	s_nop 0
	v_mul_f32_e32 v7, v6, v0
	v_lshlrev_b32_e32 v0, 16, v8
	v_mul_f32_e32 v19, v0, v0
	v_fmamk_f32 v19, v19, 0xbdd2d3e7, v129
	v_mul_f32_e32 v19, v19, v0
	v_exp_f32_e32 v19, v19
	v_mul_f32_e32 v6, v7, v7
	v_pk_add_f32 v[6:7], v[22:23], v[6:7]
	v_add_f32_e32 v19, 1.0, v19
	v_rcp_f32_e32 v19, v19
	s_nop 0
	v_mul_f32_e32 v25, v19, v0
	v_and_b32_e32 v0, 0xffff0000, v8
	v_mul_f32_e32 v8, v0, v0
	v_fmamk_f32 v8, v8, 0xbdd2d3e7, v129
	v_mul_f32_e32 v8, v8, v0
	v_exp_f32_e32 v8, v8
	v_mul_f32_e32 v24, v25, v25
	v_add_f32_e32 v8, 1.0, v8
	v_rcp_f32_e32 v8, v8
	s_nop 0
	v_mul_f32_e32 v27, v8, v0
	v_lshlrev_b32_e32 v0, 16, v9
	v_mul_f32_e32 v8, v0, v0
	v_fmamk_f32 v8, v8, 0xbdd2d3e7, v129
	v_mul_f32_e32 v8, v8, v0
	v_exp_f32_e32 v8, v8
	v_mul_f32_e32 v26, v27, v27
	v_add_f32_e32 v8, 1.0, v8
	v_rcp_f32_e32 v19, v8
	v_mul_f32_e32 v8, v28, v28
	v_fmamk_f32 v8, v8, 0xbdd2d3e7, v129
	v_mul_f32_e32 v8, v8, v28
	v_exp_f32_e32 v8, v8
	s_nop 0
	v_add_f32_e32 v8, 1.0, v8
	v_rcp_f32_e32 v29, v8
	v_pk_add_f32 v[8:9], v[16:17], v[20:21]
	s_nop 0
	v_pk_add_f32 v[8:9], v[14:15], v[8:9]
	v_mul_f32_e32 v15, v29, v28
	v_pk_add_f32 v[6:7], v[8:9], v[6:7]
	v_pk_add_f32 v[8:9], v[24:25], v[26:27]
	v_mul_f32_e32 v14, v15, v15
	v_pk_add_f32 v[6:7], v[6:7], v[8:9]
	v_mul_f32_e32 v9, v19, v0
	v_mul_f32_e32 v8, v9, v9
	v_pk_add_f32 v[8:9], v[8:9], v[14:15]
	v_lshlrev_b32_e32 v0, 16, v2
	v_pk_add_f32 v[6:7], v[6:7], v[8:9]
	v_mul_f32_e32 v8, v0, v0
	v_fmamk_f32 v8, v8, 0xbdd2d3e7, v129
	v_mul_f32_e32 v8, v8, v0
	v_exp_f32_e32 v8, v8
	v_and_b32_e32 v24, 0xffff0000, v5
	v_add_f32_e32 v8, 1.0, v8
	v_rcp_f32_e32 v8, v8
	s_nop 0
	v_mul_f32_e32 v9, v8, v0
	v_and_b32_e32 v0, 0xffff0000, v2
	v_mul_f32_e32 v2, v0, v0
	v_fmamk_f32 v2, v2, 0xbdd2d3e7, v129
	v_mul_f32_e32 v2, v2, v0
	v_exp_f32_e32 v2, v2
	v_mul_f32_e32 v8, v9, v9
	v_add_f32_e32 v2, 1.0, v2
	v_rcp_f32_e32 v2, v2
	s_nop 0
	v_mul_f32_e32 v15, v2, v0
	v_lshlrev_b32_e32 v0, 16, v3
	v_mul_f32_e32 v2, v0, v0
	v_fmamk_f32 v2, v2, 0xbdd2d3e7, v129
	v_mul_f32_e32 v2, v2, v0
	v_exp_f32_e32 v2, v2
	v_mul_f32_e32 v14, v15, v15
	v_add_f32_e32 v2, 1.0, v2
	v_rcp_f32_e32 v2, v2
	s_nop 0
	v_mul_f32_e32 v17, v2, v0
	v_and_b32_e32 v0, 0xffff0000, v3
	v_mul_f32_e32 v2, v0, v0
	v_fmamk_f32 v2, v2, 0xbdd2d3e7, v129
	v_mul_f32_e32 v2, v2, v0
	v_exp_f32_e32 v2, v2
	v_mul_f32_e32 v16, v17, v17
	v_add_f32_e32 v2, 1.0, v2
	v_rcp_f32_e32 v2, v2
	s_nop 0
	v_mul_f32_e32 v3, v2, v0
	v_lshlrev_b32_e32 v0, 16, v4
	v_mul_f32_e32 v19, v0, v0
	v_fmamk_f32 v19, v19, 0xbdd2d3e7, v129
	v_mul_f32_e32 v19, v19, v0
	v_exp_f32_e32 v19, v19
	v_mul_f32_e32 v2, v3, v3
	v_pk_add_f32 v[2:3], v[16:17], v[2:3]
	v_add_f32_e32 v19, 1.0, v19
	v_rcp_f32_e32 v19, v19
	s_nop 0
	v_mul_f32_e32 v21, v19, v0
	v_and_b32_e32 v0, 0xffff0000, v4
	v_mul_f32_e32 v4, v0, v0
	v_fmamk_f32 v4, v4, 0xbdd2d3e7, v129
	v_mul_f32_e32 v4, v4, v0
	v_exp_f32_e32 v4, v4
	v_mul_f32_e32 v20, v21, v21
	v_add_f32_e32 v4, 1.0, v4
	v_rcp_f32_e32 v4, v4
	s_nop 0
	v_mul_f32_e32 v23, v4, v0
	v_lshlrev_b32_e32 v0, 16, v5
	v_mul_f32_e32 v4, v0, v0
	v_fmamk_f32 v4, v4, 0xbdd2d3e7, v129
	v_mul_f32_e32 v4, v4, v0
	v_exp_f32_e32 v4, v4
	v_mul_f32_e32 v22, v23, v23
	v_add_f32_e32 v4, 1.0, v4
	v_rcp_f32_e32 v19, v4
	v_mul_f32_e32 v4, v24, v24
	v_fmamk_f32 v4, v4, 0xbdd2d3e7, v129
	v_mul_f32_e32 v4, v4, v24
	v_exp_f32_e32 v4, v4
	s_nop 0
	v_add_f32_e32 v4, 1.0, v4
	v_rcp_f32_e32 v25, v4
	v_pk_add_f32 v[4:5], v[8:9], v[14:15]
	s_nop 0
	v_pk_add_f32 v[4:5], v[6:7], v[4:5]
	v_mul_f32_e32 v7, v25, v24
	v_pk_add_f32 v[2:3], v[4:5], v[2:3]
	v_pk_add_f32 v[4:5], v[20:21], v[22:23]
	v_mul_f32_e32 v6, v7, v7
	v_pk_add_f32 v[2:3], v[2:3], v[4:5]
	v_mul_f32_e32 v5, v19, v0
	v_mul_f32_e32 v4, v5, v5
	v_pk_add_f32 v[4:5], v[4:5], v[6:7]
	s_nop 0
	v_pk_add_f32 v[14:15], v[2:3], v[4:5]
	s_cbranch_scc1 .LBB0_621
	v_and_b32_e32 v171, 0xff, v194
	v_lshlrev_b32_e32 v171, 3, v171
	s_mul_i32 s66, s64, 0x12000
	s_add_i32 s66, s66, 0x11000
	s_xor_b32 s67, s64, 1
	s_mul_i32 s67, s67, 0x12000
	s_add_i32 s67, s67, 0x11000
	v_add_u32_e32 v172, s66, v171
	v_add_u32_e32 v173, s67, v171
	ds_write_b64 v172, v[14:15]
	s_waitcnt lgkmcnt(0)
	s_barrier
	ds_read_b64 v[174:175], v173
	s_waitcnt lgkmcnt(0)
	v_add_f32_e32 v14, v14, v174
	v_add_f32_e32 v15, v15, v175
	v_readlane_b32 s0, v254, 51
	s_lshl_b32 s88, s0, 9
	v_readlane_b32 s40, v251, 6
	s_lshl_b64 s[6:7], s[88:89], 2
	v_readlane_b32 s52, v251, 18
	v_readlane_b32 s53, v251, 19
	s_add_u32 s1, s52, s6
	s_addc_u32 s2, s53, s7
	s_lshl_b32 s0, s10, 7
	s_and_b32 s0, s0, 0x180
	s_lshl_b32 s5, s0, 2
	s_add_u32 s16, s1, s5
	v_readlane_b32 s54, v251, 20
	s_addc_u32 s17, s2, 0
	v_readlane_b32 s55, v251, 21
	s_add_u32 s1, s54, s6
	s_addc_u32 s2, s55, s7
	s_add_u32 s20, s1, s5
	s_addc_u32 s21, s2, 0
	s_lshl_b32 s8, s0, 1
	s_mov_b32 s9, s89
	v_lshl_add_u64 v[2:3], v[10:11], 0, s[8:9]
	v_lshlrev_b32_e32 v0, 7, v18
	v_lshl_add_u64 v[22:23], v[2:3], 0, v[0:1]
	global_load_dwordx4 v[10:13], v[22:23], off offset:1024
	v_lshlrev_b32_e32 v20, 8, v18
	global_load_dwordx2 v[28:29], v20, s[16:17]
	global_load_dwordx2 v[36:37], v20, s[20:21]
	global_load_dwordx2 v[40:41], v20, s[16:17] offset:16
	global_load_dwordx2 v[42:43], v20, s[16:17] offset:32
	global_load_dwordx2 v[24:25], v20, s[16:17] offset:48
	global_load_dwordx2 v[44:45], v20, s[20:21] offset:16
	global_load_dwordx2 v[46:47], v20, s[20:21] offset:32
	global_load_dwordx2 v[26:27], v20, s[20:21] offset:48
	v_xor_b32_e32 v2, 1, v234
	v_cmp_lt_i32_e32 vcc, v2, v235
	s_mov_b32 s2, 0x3b000000
	v_lshlrev_b32_e32 v34, 6, v18
	v_cndmask_b32_e32 v2, v234, v2, vcc
	v_lshlrev_b32_e32 v80, 2, v2
	ds_bpermute_b32 v3, v80, v15
	ds_bpermute_b32 v2, v80, v14
	v_mul_u32_u24_e32 v4, 0x4400, v18
	v_lshlrev_b32_e32 v33, 1, v31
	s_mov_b32 s11, 0x800000
	v_add3_u32 v38, s15, v4, v33
	s_waitcnt lgkmcnt(0)
	v_pk_add_f32 v[2:3], v[14:15], v[2:3]
	v_or_b32_e32 v4, 1, v34
	v_pk_mul_f32 v[18:19], v[2:3], s[2:3] op_sel_hi:[1,0]
	v_mul_u32_u24_e32 v4, 0x110, v4
	v_fma_f32 v2, -v19, v19, v18
	v_max_f32_e32 v2, 0, v2
	v_add_f32_e32 v2, 0x358637bd, v2
	v_mul_f32_e32 v3, 0x4b800000, v2
	v_cmp_gt_f32_e32 vcc, s11, v2
	v_add3_u32 v35, s15, v4, v33
	v_or_b32_e32 v78, 7, v34
	v_cndmask_b32_e32 v2, v2, v3, vcc
	v_rsq_f32_e32 v18, v2
	global_load_dwordx4 v[14:17], v[22:23], off offset:1040
	global_load_dwordx4 v[2:5], v[22:23], off offset:1072
	global_load_dwordx4 v[6:9], v[22:23], off offset:1056
	v_or_b32_e32 v81, 10, v34
	v_or_b32_e32 v79, 11, v34
	v_mul_f32_e32 v39, 0x45800000, v18
	v_cndmask_b32_e32 v39, v18, v39, vcc
	v_readlane_b32 s41, v251, 7
	v_readlane_b32 s42, v251, 8
	v_readlane_b32 s43, v251, 9
	v_readlane_b32 s44, v251, 10
	v_readlane_b32 s45, v251, 11
	v_readlane_b32 s46, v251, 12
	v_readlane_b32 s47, v251, 13
	v_readlane_b32 s48, v251, 14
	v_readlane_b32 s49, v251, 15
	v_readlane_b32 s50, v251, 16
	v_readlane_b32 s51, v251, 17
	s_or_b32 s88, s0, s88
	v_readlane_b32 s40, v251, 22
	v_readlane_b32 s41, v251, 23
	v_mov_b32_e32 v21, v1
	v_mul_u32_u24_e32 v84, 0x110, v31
	v_add3_u32 v0, s15, v84, v0
	v_or_b32_e32 v101, 31, v34
	v_cmp_gt_u32_e32 vcc, v31, v34
	v_or_b32_e32 v57, 48, v34
	v_and_b32_e32 v32, 15, v50
	v_readlane_b32 s44, v251, 26
	v_readlane_b32 s45, v251, 27
	v_readlane_b32 s46, v251, 28
	v_readlane_b32 s47, v251, 29
	v_readlane_b32 s48, v251, 30
	v_readlane_b32 s49, v251, 31
	v_readlane_b32 s50, v251, 32
	v_readlane_b32 s51, v251, 33
	v_readlane_b32 s52, v251, 34
	v_readlane_b32 s53, v251, 35
	v_readlane_b32 s54, v251, 36
	v_readlane_b32 s55, v251, 37
	v_readlane_b32 s44, v251, 54
	v_readlane_b32 s50, v251, 60
	v_readlane_b32 s51, v251, 61
	s_add_u32 s6, s50, s8
	s_addc_u32 s7, s51, 0
	v_readlane_b32 s42, v251, 24
	v_readlane_b32 s43, v251, 25
	v_readlane_b32 s52, v251, 62
	v_readlane_b32 s53, v251, 63
	v_readlane_b32 s54, v252, 0
	v_readlane_b32 s55, v252, 1
	v_readlane_b32 s45, v251, 55
	s_waitcnt vmcnt(11)
	v_lshlrev_b32_e32 v48, 16, v11
	v_and_b32_e32 v11, 0xffff0000, v11
	v_mul_f32_e32 v54, v11, v11
	v_fmamk_f32 v54, v54, 0xbdd2d3e7, v129
	v_mul_f32_e32 v54, v54, v11
	v_lshlrev_b32_e32 v18, 16, v10
	v_and_b32_e32 v10, 0xffff0000, v10
	v_mul_f32_e32 v51, v18, v18
	v_mul_f32_e32 v52, v10, v10
	v_fmamk_f32 v51, v51, 0xbdd2d3e7, v129
	v_exp_f32_e32 v54, v54
	v_fmamk_f32 v52, v52, 0xbdd2d3e7, v129
	v_mul_f32_e32 v51, v51, v18
	v_mul_f32_e32 v52, v52, v10
	v_exp_f32_e32 v51, v51
	v_add_f32_e32 v54, 1.0, v54
	v_exp_f32_e32 v52, v52
	v_rcp_f32_e32 v54, v54
	v_lshlrev_b32_e32 v49, 16, v12
	v_mul_f32_e32 v55, v49, v49
	v_fmamk_f32 v55, v55, 0xbdd2d3e7, v129
	v_add_f32_e32 v51, 1.0, v51
	v_mul_f32_e32 v55, v55, v49
	v_add_f32_e32 v52, 1.0, v52
	v_rcp_f32_e32 v51, v51
	v_fma_f32 v11, v54, v11, -v19
	v_rcp_f32_e32 v52, v52
	v_mul_f32_e32 v59, v39, v11
	v_and_b32_e32 v11, 0xffff0000, v12
	v_mul_f32_e32 v12, v11, v11
	v_exp_f32_e32 v55, v55
	v_fmamk_f32 v12, v12, 0xbdd2d3e7, v129
	v_fma_f32 v18, v51, v18, -v19
	v_mul_f32_e32 v12, v12, v11
	v_fma_f32 v10, v52, v10, -v19
	v_mul_f32_e32 v18, v39, v18
	v_mul_f32_e32 v10, v39, v10
	s_waitcnt vmcnt(9)
	v_fma_f32 v18, v28, v18, v36
	v_lshlrev_b32_e32 v28, 16, v13
	v_add_f32_e32 v55, 1.0, v55
	v_fmac_f32_e32 v37, v29, v10
	v_exp_f32_e32 v12, v12
	v_mul_f32_e32 v29, v28, v28
	v_rcp_f32_e32 v55, v55
	v_fmamk_f32 v29, v29, 0xbdd2d3e7, v129
	v_mul_f32_e32 v29, v29, v28
	v_cvt_pk_bf16_f32 v10, v18, s0
	v_add_f32_e32 v12, 1.0, v12
	v_cvt_pk_bf16_f32 v18, v37, s0
	ds_write_b16 v38, v10 offset:34816
	ds_write_b16 v35, v18 offset:34816
	v_fma_f32 v10, v55, v49, -v19
	v_rcp_f32_e32 v12, v12
	v_exp_f32_e32 v29, v29
	v_mul_f32_e32 v10, v39, v10
	s_waitcnt vmcnt(5)
	v_fma_f32 v10, v40, v10, v44
	v_cvt_pk_bf16_f32 v10, v10, s0
	ds_write_b16 v35, v10 offset:35632
	v_fma_f32 v10, v12, v11, -v19
	v_add_f32_e32 v11, 1.0, v29
	v_rcp_f32_e32 v11, v11
	v_mul_f32_e32 v10, v39, v10
	v_fmac_f32_e32 v45, v10, v41
	v_cvt_pk_bf16_f32 v10, v45, s0
	ds_write_b16 v35, v10 offset:35904
	v_fma_f32 v10, v11, v28, -v19
	v_and_b32_e32 v11, 0xffff0000, v13
	v_mul_f32_e32 v12, v11, v11
	v_fmamk_f32 v12, v12, 0xbdd2d3e7, v129
	v_mul_f32_e32 v12, v12, v11
	v_exp_f32_e32 v12, v12
	s_waitcnt vmcnt(2)
	v_lshlrev_b32_e32 v13, 16, v14
	v_mul_f32_e32 v28, v13, v13
	v_fmamk_f32 v28, v28, 0xbdd2d3e7, v129
	v_add_f32_e32 v12, 1.0, v12
	v_rcp_f32_e32 v12, v12
	v_mul_f32_e32 v28, v28, v13
	v_fma_f32 v11, v12, v11, -v19
	v_exp_f32_e32 v28, v28
	v_mul_f32_e32 v44, v39, v11
	v_and_b32_e32 v11, 0xffff0000, v14
	v_mul_f32_e32 v12, v11, v11
	v_fmamk_f32 v12, v12, 0xbdd2d3e7, v129
	v_mul_f32_e32 v12, v12, v11
	v_mul_f32_e32 v45, v39, v10
	v_add_f32_e32 v10, 1.0, v28
	v_rcp_f32_e32 v10, v10
	v_exp_f32_e32 v12, v12
	v_lshlrev_b32_e32 v29, 16, v16
	v_fma_f32 v10, v10, v13, -v19
	v_lshlrev_b32_e32 v13, 16, v15
	v_add_f32_e32 v12, 1.0, v12
	v_mul_f32_e32 v14, v13, v13
	v_rcp_f32_e32 v12, v12
	v_fmamk_f32 v14, v14, 0xbdd2d3e7, v129
	v_mul_f32_e32 v10, v39, v10
	v_mul_f32_e32 v14, v14, v13
	v_fma_f32 v10, v42, v10, v46
	v_cvt_pk_bf16_f32 v10, v10, s0
	v_exp_f32_e32 v14, v14
	ds_write_b16 v35, v10 offset:36720
	v_fma_f32 v10, v12, v11, -v19
	v_mul_f32_e32 v10, v39, v10
	v_fmac_f32_e32 v47, v43, v10
	v_cvt_pk_bf16_f32 v10, v47, s0
	v_and_b32_e32 v15, 0xffff0000, v15
	v_add_f32_e32 v11, 1.0, v14
	ds_write_b16 v35, v10 offset:36992
	v_mul_f32_e32 v10, v15, v15
	v_rcp_f32_e32 v11, v11
	v_fmamk_f32 v10, v10, 0xbdd2d3e7, v129
	v_mul_f32_e32 v10, v10, v15
	v_fma_f32 v14, v11, v13, -v19
	v_exp_f32_e32 v28, v10
	global_load_dwordx2 v[10:11], v20, s[16:17] offset:64
	global_load_dwordx2 v[12:13], v20, s[20:21] offset:64
	v_mul_f32_e32 v37, v29, v29
	v_fmamk_f32 v37, v37, 0xbdd2d3e7, v129
	v_add_f32_e32 v28, 1.0, v28
	v_mul_f32_e32 v37, v37, v29
	v_rcp_f32_e32 v28, v28
	v_exp_f32_e32 v37, v37
	v_fma_f32 v15, v28, v15, -v19
	v_mul_f32_e32 v46, v39, v15
	v_and_b32_e32 v15, 0xffff0000, v16
	v_mul_f32_e32 v16, v15, v15
	v_mul_f32_e32 v47, v39, v14
	v_add_f32_e32 v14, 1.0, v37
	v_fmamk_f32 v16, v16, 0xbdd2d3e7, v129
	v_rcp_f32_e32 v14, v14
	v_mul_f32_e32 v16, v16, v15
	v_exp_f32_e32 v16, v16
	v_fma_f32 v14, v14, v29, -v19
	v_mul_f32_e32 v14, v39, v14
	v_fma_f32 v14, v24, v14, v26
	v_lshlrev_b32_e32 v24, 16, v17
	v_add_f32_e32 v16, 1.0, v16
	v_mul_f32_e32 v26, v24, v24
	v_rcp_f32_e32 v16, v16
	v_fmamk_f32 v26, v26, 0xbdd2d3e7, v129
	v_mul_f32_e32 v26, v26, v24
	v_cvt_pk_bf16_f32 v14, v14, s0
	v_exp_f32_e32 v26, v26
	ds_write_b16 v35, v14 offset:37808
	v_fma_f32 v14, v16, v15, -v19
	v_mul_f32_e32 v14, v39, v14
	v_fmac_f32_e32 v27, v14, v25
	v_cvt_pk_bf16_f32 v14, v27, s0
	v_and_b32_e32 v25, 0xffff0000, v17
	v_add_f32_e32 v15, 1.0, v26
	ds_write_b16 v35, v14 offset:38080
	v_mul_f32_e32 v14, v25, v25
	v_rcp_f32_e32 v15, v15
	v_fmamk_f32 v14, v14, 0xbdd2d3e7, v129
	v_mul_f32_e32 v14, v14, v25
	v_fma_f32 v24, v15, v24, -v19
	v_exp_f32_e32 v26, v14
	global_load_dwordx2 v[14:15], v20, s[16:17] offset:80
	global_load_dwordx2 v[16:17], v20, s[20:21] offset:80
	s_waitcnt vmcnt(4)
	v_lshlrev_b32_e32 v27, 16, v6
	v_mul_f32_e32 v28, v27, v27
	v_fmamk_f32 v28, v28, 0xbdd2d3e7, v129
	v_mul_f32_e32 v28, v28, v27
	v_exp_f32_e32 v28, v28
	v_mul_f32_e32 v55, v39, v24
	v_mul_f32_e32 v53, v48, v48
	v_fmamk_f32 v53, v53, 0xbdd2d3e7, v129
	v_add_f32_e32 v24, 1.0, v28
	v_rcp_f32_e32 v24, v24
	v_and_b32_e32 v6, 0xffff0000, v6
	v_mul_f32_e32 v53, v53, v48
	v_fma_f32 v24, v24, v27, -v19
	v_mul_f32_e32 v40, v39, v24
	v_mul_f32_e32 v24, v6, v6
	v_fmamk_f32 v24, v24, 0xbdd2d3e7, v129
	v_mul_f32_e32 v24, v24, v6
	v_exp_f32_e32 v53, v53
	v_exp_f32_e32 v41, v24
	v_add_f32_e32 v53, 1.0, v53
	v_add_f32_e32 v26, 1.0, v26
	v_rcp_f32_e32 v53, v53
	v_rcp_f32_e32 v26, v26
	s_waitcnt vmcnt(2)
	v_fma_f32 v10, v10, v40, v12
	v_lshlrev_b32_e32 v40, 16, v7
	v_add_f32_e32 v12, 1.0, v41
	v_mul_f32_e32 v41, v40, v40
	v_fmamk_f32 v41, v41, 0xbdd2d3e7, v129
	v_mul_f32_e32 v41, v41, v40
	v_fma_f32 v48, v53, v48, -v19
	v_fma_f32 v25, v26, v25, -v19
	v_mul_f32_e32 v65, v39, v48
	v_mul_f32_e32 v54, v39, v25
	global_load_dwordx2 v[24:25], v20, s[16:17] offset:96
	global_load_dwordx2 v[28:29], v20, s[16:17] offset:112
	global_load_dwordx2 v[26:27], v20, s[20:21] offset:96
	global_load_dwordx2 v[48:49], v20, s[20:21] offset:112
	v_exp_f32_e32 v41, v41
	v_rcp_f32_e32 v12, v12
	v_cvt_pk_bf16_f32 v10, v10, s0
	ds_write_b16 v35, v10 offset:38896
	v_add_f32_e32 v10, 1.0, v41
	v_fma_f32 v6, v12, v6, -v19
	v_rcp_f32_e32 v10, v10
	v_mul_f32_e32 v6, v39, v6
	v_fmac_f32_e32 v13, v11, v6
	v_cvt_pk_bf16_f32 v6, v13, s0
	v_and_b32_e32 v7, 0xffff0000, v7
	ds_write_b16 v35, v6 offset:39168
	v_fma_f32 v6, v10, v40, -v19
	v_mul_f32_e32 v10, v7, v7
	v_fmamk_f32 v10, v10, 0xbdd2d3e7, v129
	v_mul_f32_e32 v10, v10, v7
	v_exp_f32_e32 v10, v10
	v_lshlrev_b32_e32 v11, 16, v8
	v_mul_f32_e32 v12, v11, v11
	v_fmamk_f32 v12, v12, 0xbdd2d3e7, v129
	v_mul_f32_e32 v12, v12, v11
	v_add_f32_e32 v10, 1.0, v10
	v_rcp_f32_e32 v10, v10
	v_exp_f32_e32 v12, v12
	v_mul_f32_e32 v53, v39, v6
	v_fma_f32 v7, v10, v7, -v19
	v_mul_f32_e32 v52, v39, v7
	v_and_b32_e32 v7, 0xffff0000, v8
	v_add_f32_e32 v6, 1.0, v12
	v_mul_f32_e32 v8, v7, v7
	v_rcp_f32_e32 v6, v6
	v_fmamk_f32 v8, v8, 0xbdd2d3e7, v129
	v_mul_f32_e32 v8, v8, v7
	v_lshlrev_b32_e32 v10, 16, v9
	v_fma_f32 v6, v6, v11, -v19
	v_exp_f32_e32 v8, v8
	v_mul_f32_e32 v11, v10, v10
	v_fmamk_f32 v11, v11, 0xbdd2d3e7, v129
	v_mul_f32_e32 v11, v11, v10
	v_add_f32_e32 v8, 1.0, v8
	v_rcp_f32_e32 v8, v8
	v_exp_f32_e32 v11, v11
	v_mul_f32_e32 v6, v39, v6
	s_waitcnt vmcnt(4)
	v_fma_f32 v6, v14, v6, v16
	v_cvt_pk_bf16_f32 v6, v6, s0
	ds_write_b16 v35, v6 offset:39984
	v_fma_f32 v6, v8, v7, -v19
	v_add_f32_e32 v7, 1.0, v11
	v_rcp_f32_e32 v7, v7
	v_mul_f32_e32 v6, v39, v6
	v_fmac_f32_e32 v17, v6, v15
	v_cvt_pk_bf16_f32 v6, v17, s0
	ds_write_b16 v35, v6 offset:40256
	v_fma_f32 v6, v7, v10, -v19
	v_and_b32_e32 v7, 0xffff0000, v9
	v_lshlrev_b32_e32 v9, 16, v2
	v_mul_f32_e32 v10, v9, v9
	v_fmamk_f32 v10, v10, 0xbdd2d3e7, v129
	v_mul_f32_e32 v8, v7, v7
	v_mul_f32_e32 v10, v10, v9
	v_fmamk_f32 v8, v8, 0xbdd2d3e7, v129
	v_mul_f32_e32 v8, v8, v7
	v_exp_f32_e32 v10, v10
	v_exp_f32_e32 v8, v8
	v_mul_f32_e32 v58, v39, v6
	v_add_f32_e32 v6, 1.0, v10
	global_load_dwordx4 v[10:13], v[22:23], off offset:1104
	global_load_dwordx4 v[14:17], v[22:23], off offset:1088
	v_add_f32_e32 v8, 1.0, v8
	v_rcp_f32_e32 v8, v8
	v_and_b32_e32 v2, 0xffff0000, v2
	v_rcp_f32_e32 v6, v6
	v_or_b32_e32 v18, 4, v34
	v_fma_f32 v7, v8, v7, -v19
	v_mul_f32_e32 v56, v39, v7
	v_mul_f32_e32 v7, v2, v2
	v_fmamk_f32 v7, v7, 0xbdd2d3e7, v129
	v_mul_f32_e32 v7, v7, v2
	v_exp_f32_e32 v7, v7
	v_lshlrev_b32_e32 v8, 16, v3
	v_fma_f32 v6, v6, v9, -v19
	v_mul_f32_e32 v9, v8, v8
	v_add_f32_e32 v7, 1.0, v7
	v_rcp_f32_e32 v7, v7
	v_fmamk_f32 v9, v9, 0xbdd2d3e7, v129
	v_mul_f32_e32 v9, v9, v8
	v_fma_f32 v2, v7, v2, -v19
	v_mul_f32_e32 v6, v39, v6
	v_mul_f32_e32 v2, v39, v2
	s_waitcnt vmcnt(3)
	v_fma_f32 v6, v24, v6, v26
	v_exp_f32_e32 v9, v9
	v_fmac_f32_e32 v27, v25, v2
	v_cvt_pk_bf16_f32 v6, v6, s0
	v_cvt_pk_bf16_f32 v2, v27, s0
	ds_write_b16 v35, v6 offset:41072
	ds_write_b16 v35, v2 offset:41344
	global_load_dwordx2 v[24:25], v20, s[16:17] offset:128
	global_load_dwordx2 v[26:27], v20, s[20:21] offset:128
	v_add_f32_e32 v6, 1.0, v9
	v_rcp_f32_e32 v6, v6
	v_and_b32_e32 v3, 0xffff0000, v3
	v_lshlrev_b32_e32 v7, 16, v4
	v_or_b32_e32 v36, 8, v34
	v_fma_f32 v2, v6, v8, -v19
	v_mul_f32_e32 v6, v3, v3
	v_fmamk_f32 v6, v6, 0xbdd2d3e7, v129
	v_mul_f32_e32 v6, v6, v3
	v_exp_f32_e32 v6, v6
	v_mul_f32_e32 v8, v7, v7
	v_fmamk_f32 v8, v8, 0xbdd2d3e7, v129
	v_mul_f32_e32 v8, v8, v7
	v_add_f32_e32 v6, 1.0, v6
	v_rcp_f32_e32 v6, v6
	v_exp_f32_e32 v8, v8
	v_mul_f32_e32 v64, v39, v2
	v_fma_f32 v3, v6, v3, -v19
	v_mul_f32_e32 v63, v39, v3
	v_and_b32_e32 v3, 0xffff0000, v4
	v_add_f32_e32 v2, 1.0, v8
	v_mul_f32_e32 v4, v3, v3
	v_rcp_f32_e32 v2, v2
	v_fmamk_f32 v4, v4, 0xbdd2d3e7, v129
	v_mul_f32_e32 v4, v4, v3
	v_fma_f32 v2, v2, v7, -v19
	v_exp_f32_e32 v4, v4
	v_mul_f32_e32 v2, v39, v2
	s_waitcnt vmcnt(4)
	v_fma_f32 v2, v28, v2, v48
	v_cvt_pk_bf16_f32 v2, v2, s0
	ds_write_b16 v35, v2 offset:42160
	v_add_f32_e32 v2, 1.0, v4
	v_lshlrev_b32_e32 v4, 16, v5
	v_mul_f32_e32 v6, v4, v4
	v_fmamk_f32 v6, v6, 0xbdd2d3e7, v129
	v_rcp_f32_e32 v2, v2
	v_mul_f32_e32 v6, v6, v4
	v_exp_f32_e32 v6, v6
	v_fma_f32 v2, v2, v3, -v19
	v_mul_f32_e32 v2, v39, v2
	v_fmac_f32_e32 v49, v2, v29
	v_add_f32_e32 v2, 1.0, v6
	v_cvt_pk_bf16_f32 v6, v49, s0
	ds_write_b16 v35, v6 offset:42432
	global_load_dwordx2 v[60:61], v20, s[16:17] offset:144
	global_load_dwordx2 v[66:67], v20, s[20:21] offset:144
	v_and_b32_e32 v3, 0xffff0000, v5
	v_mul_f32_e32 v5, v3, v3
	v_fmamk_f32 v5, v5, 0xbdd2d3e7, v129
	v_mul_f32_e32 v5, v5, v3
	v_rcp_f32_e32 v2, v2
	v_exp_f32_e32 v5, v5
	s_waitcnt vmcnt(4)
	v_lshlrev_b32_e32 v28, 16, v14
	v_and_b32_e32 v14, 0xffff0000, v14
	v_fma_f32 v2, v2, v4, -v19
	v_add_f32_e32 v4, 1.0, v5
	v_mul_f32_e32 v5, v28, v28
	v_fmamk_f32 v5, v5, 0xbdd2d3e7, v129
	v_mul_f32_e32 v5, v5, v28
	v_rcp_f32_e32 v4, v4
	v_exp_f32_e32 v5, v5
	v_mul_f32_e32 v69, v39, v2
	v_fma_f32 v2, v4, v3, -v19
	v_mul_f32_e32 v68, v39, v2
	v_add_f32_e32 v2, 1.0, v5
	v_rcp_f32_e32 v29, v2
	global_load_dwordx4 v[2:5], v[22:23], off offset:1136
	global_load_dwordx4 v[6:9], v[22:23], off offset:1120
	v_or_b32_e32 v37, 12, v34
	v_or_b32_e32 v38, 16, v34
	v_fma_f32 v22, v29, v28, -v19
	v_mul_f32_e32 v48, v39, v22
	v_mul_f32_e32 v22, v14, v14
	v_fmamk_f32 v22, v22, 0xbdd2d3e7, v129
	v_mul_f32_e32 v22, v22, v14
	v_exp_f32_e32 v49, v22
	global_load_dwordx2 v[74:75], v20, s[16:17] offset:160
	global_load_dwordx2 v[22:23], v20, s[16:17] offset:176
	global_load_dwordx2 v[76:77], v20, s[20:21] offset:160
	global_load_dwordx2 v[28:29], v20, s[20:21] offset:176
	s_waitcnt vmcnt(8)
	v_fma_f32 v24, v24, v48, v26
	v_lshlrev_b32_e32 v48, 16, v15
	v_add_f32_e32 v26, 1.0, v49
	v_mul_f32_e32 v49, v48, v48
	v_fmamk_f32 v49, v49, 0xbdd2d3e7, v129
	v_mul_f32_e32 v49, v49, v48
	v_exp_f32_e32 v49, v49
	v_rcp_f32_e32 v26, v26
	v_cvt_pk_bf16_f32 v24, v24, s0
	ds_write_b16 v35, v24 offset:43248
	v_add_f32_e32 v24, 1.0, v49
	v_fma_f32 v14, v26, v14, -v19
	v_rcp_f32_e32 v24, v24
	v_mul_f32_e32 v14, v39, v14
	v_fmac_f32_e32 v27, v25, v14
	v_cvt_pk_bf16_f32 v14, v27, s0
	v_and_b32_e32 v15, 0xffff0000, v15
	ds_write_b16 v35, v14 offset:43520
	v_fma_f32 v14, v24, v48, -v19
	v_mul_f32_e32 v24, v15, v15
	v_fmamk_f32 v24, v24, 0xbdd2d3e7, v129
	v_mul_f32_e32 v24, v24, v15
	v_exp_f32_e32 v24, v24
	v_lshlrev_b32_e32 v25, 16, v16
	v_mul_f32_e32 v26, v25, v25
	v_fmamk_f32 v26, v26, 0xbdd2d3e7, v129
	v_mul_f32_e32 v26, v26, v25
	v_add_f32_e32 v24, 1.0, v24
	v_rcp_f32_e32 v24, v24
	v_exp_f32_e32 v26, v26
	v_mul_f32_e32 v73, v39, v14
	v_fma_f32 v15, v24, v15, -v19
	v_mul_f32_e32 v72, v39, v15
	v_and_b32_e32 v15, 0xffff0000, v16
	v_add_f32_e32 v14, 1.0, v26
	v_mul_f32_e32 v16, v15, v15
	v_rcp_f32_e32 v14, v14
	v_fmamk_f32 v16, v16, 0xbdd2d3e7, v129
	v_mul_f32_e32 v16, v16, v15
	v_lshlrev_b32_e32 v24, 16, v17
	v_fma_f32 v14, v14, v25, -v19
	v_exp_f32_e32 v16, v16
	v_mul_f32_e32 v25, v24, v24
	v_fmamk_f32 v25, v25, 0xbdd2d3e7, v129
	v_mul_f32_e32 v25, v25, v24
	v_add_f32_e32 v16, 1.0, v16
	v_rcp_f32_e32 v16, v16
	v_exp_f32_e32 v25, v25
	v_mul_f32_e32 v14, v39, v14
	s_waitcnt vmcnt(6)
	v_fma_f32 v14, v60, v14, v66
	v_cvt_pk_bf16_f32 v14, v14, s0
	ds_write_b16 v35, v14 offset:44336
	v_fma_f32 v14, v16, v15, -v19
	v_add_f32_e32 v15, 1.0, v25
	v_rcp_f32_e32 v15, v15
	v_mul_f32_e32 v14, v39, v14
	v_fmac_f32_e32 v67, v14, v61
	v_cvt_pk_bf16_f32 v14, v67, s0
	ds_write_b16 v35, v14 offset:44608
	v_fma_f32 v14, v15, v24, -v19
	v_and_b32_e32 v15, 0xffff0000, v17
	v_mul_f32_e32 v16, v15, v15
	v_fmamk_f32 v16, v16, 0xbdd2d3e7, v129
	v_mul_f32_e32 v16, v16, v15
	v_exp_f32_e32 v16, v16
	v_lshlrev_b32_e32 v17, 16, v10
	v_mul_f32_e32 v24, v17, v17
	v_fmamk_f32 v24, v24, 0xbdd2d3e7, v129
	v_mul_f32_e32 v24, v24, v17
	v_add_f32_e32 v16, 1.0, v16
	v_rcp_f32_e32 v16, v16
	v_exp_f32_e32 v24, v24
	v_and_b32_e32 v10, 0xffff0000, v10
	v_mul_f32_e32 v71, v39, v14
	v_fma_f32 v15, v16, v15, -v19
	v_add_f32_e32 v14, 1.0, v24
	v_mul_f32_e32 v70, v39, v15
	v_mul_f32_e32 v15, v10, v10
	v_rcp_f32_e32 v14, v14
	v_fmamk_f32 v15, v15, 0xbdd2d3e7, v129
	v_mul_f32_e32 v15, v15, v10
	v_fma_f32 v14, v14, v17, -v19
	v_exp_f32_e32 v15, v15
	v_mul_f32_e32 v14, v39, v14
	s_waitcnt vmcnt(1)
	v_fma_f32 v14, v74, v14, v76
	v_cvt_pk_bf16_f32 v14, v14, s0
	ds_write_b16 v35, v14 offset:45424
	v_add_f32_e32 v14, 1.0, v15
	v_lshlrev_b32_e32 v15, 16, v11
	v_rcp_f32_e32 v14, v14
	v_mul_f32_e32 v16, v15, v15
	v_fmamk_f32 v16, v16, 0xbdd2d3e7, v129
	v_mul_f32_e32 v16, v16, v15
	v_and_b32_e32 v11, 0xffff0000, v11
	v_fma_f32 v10, v14, v10, -v19
	v_mul_f32_e32 v14, v11, v11
	v_exp_f32_e32 v16, v16
	v_fmamk_f32 v14, v14, 0xbdd2d3e7, v129
	v_mul_f32_e32 v14, v14, v11
	v_mul_f32_e32 v10, v39, v10
	v_fmac_f32_e32 v77, v75, v10
	v_add_f32_e32 v10, 1.0, v16
	v_exp_f32_e32 v14, v14
	v_rcp_f32_e32 v10, v10
	v_cvt_pk_bf16_f32 v16, v77, s0
	ds_write_b16 v35, v16 offset:45696
	v_add_f32_e32 v14, 1.0, v14
	v_fma_f32 v10, v10, v15, -v19
	v_rcp_f32_e32 v14, v14
	v_lshlrev_b32_e32 v15, 16, v12
	v_mul_f32_e32 v16, v15, v15
	v_fmamk_f32 v16, v16, 0xbdd2d3e7, v129
	v_mul_f32_e32 v16, v16, v15
	v_mul_f32_e32 v67, v39, v10
	v_fma_f32 v10, v14, v11, -v19
	v_and_b32_e32 v11, 0xffff0000, v12
	v_mul_f32_e32 v12, v11, v11
	v_exp_f32_e32 v16, v16
	v_fmamk_f32 v12, v12, 0xbdd2d3e7, v129
	v_mul_f32_e32 v12, v12, v11
	v_mul_f32_e32 v66, v39, v10
	v_add_f32_e32 v10, 1.0, v16
	v_exp_f32_e32 v12, v12
	v_rcp_f32_e32 v10, v10
	v_or_b32_e32 v76, 2, v34
	v_lshlrev_b32_e32 v14, 2, v76
	v_add_f32_e32 v12, 1.0, v12
	v_fma_f32 v10, v10, v15, -v19
	v_rcp_f32_e32 v12, v12
	v_mul_f32_e32 v10, v39, v10
	s_waitcnt vmcnt(0)
	v_fma_f32 v10, v22, v10, v28
	v_cvt_pk_bf16_f32 v10, v10, s0
	ds_write_b16 v35, v10 offset:46512
	v_fma_f32 v10, v12, v11, -v19
	v_lshlrev_b32_e32 v11, 16, v13
	v_mul_f32_e32 v12, v11, v11
	v_fmamk_f32 v12, v12, 0xbdd2d3e7, v129
	v_mul_f32_e32 v12, v12, v11
	v_exp_f32_e32 v12, v12
	v_mul_f32_e32 v10, v39, v10
	v_fmac_f32_e32 v29, v10, v23
	v_cvt_pk_bf16_f32 v10, v29, s0
	global_load_dword v15, v14, s[16:17]
	s_nop 0
	global_load_dword v14, v14, s[20:21]
	ds_write_b16 v35, v10 offset:46784
	v_add_f32_e32 v10, 1.0, v12
	v_rcp_f32_e32 v10, v10
	v_or_b32_e32 v77, 3, v34
	v_lshlrev_b32_e32 v12, 2, v77
	global_load_dword v16, v12, s[16:17]
	global_load_dword v17, v12, s[20:21]
	v_fma_f32 v10, v10, v11, -v19
	v_and_b32_e32 v11, 0xffff0000, v13
	v_mul_f32_e32 v12, v11, v11
	v_fmamk_f32 v12, v12, 0xbdd2d3e7, v129
	v_mul_f32_e32 v12, v12, v11
	v_lshlrev_b32_e32 v13, 16, v6
	v_exp_f32_e32 v12, v12
	v_mul_f32_e32 v22, v13, v13
	v_fmamk_f32 v22, v22, 0xbdd2d3e7, v129
	v_mul_f32_e32 v22, v22, v13
	v_add_f32_e32 v12, 1.0, v12
	v_exp_f32_e32 v22, v22
	v_rcp_f32_e32 v12, v12
	v_mul_f32_e32 v75, v39, v10
	v_and_b32_e32 v6, 0xffff0000, v6
	v_add_f32_e32 v10, 1.0, v22
	v_fma_f32 v11, v12, v11, -v19
	v_rcp_f32_e32 v10, v10
	v_mul_f32_e32 v74, v39, v11
	v_mul_f32_e32 v11, v6, v6
	v_fmamk_f32 v11, v11, 0xbdd2d3e7, v129
	v_mul_f32_e32 v11, v11, v6
	v_fma_f32 v10, v10, v13, -v19
	v_exp_f32_e32 v22, v11
	v_mul_f32_e32 v82, v39, v10
	global_load_dwordx2 v[10:11], v20, s[16:17] offset:192
	global_load_dwordx2 v[12:13], v20, s[20:21] offset:192
	v_lshlrev_b32_e32 v23, 16, v7
	v_mul_f32_e32 v24, v23, v23
	v_and_b32_e32 v7, 0xffff0000, v7
	v_fmamk_f32 v24, v24, 0xbdd2d3e7, v129
	v_mul_f32_e32 v25, v7, v7
	v_mul_f32_e32 v24, v24, v23
	v_fmamk_f32 v25, v25, 0xbdd2d3e7, v129
	v_mul_f32_e32 v25, v25, v7
	v_add_f32_e32 v22, 1.0, v22
	v_rcp_f32_e32 v22, v22
	v_exp_f32_e32 v24, v24
	v_exp_f32_e32 v25, v25
	v_fma_f32 v6, v22, v6, -v19
	v_add_f32_e32 v22, 1.0, v24
	v_rcp_f32_e32 v22, v22
	v_add_f32_e32 v24, 1.0, v25
	v_rcp_f32_e32 v24, v24
	v_mul_f32_e32 v83, v39, v6
	v_fma_f32 v6, v22, v23, -v19
	v_mul_f32_e32 v62, v39, v6
	v_fma_f32 v6, v24, v7, -v19
	v_lshlrev_b32_e32 v91, 16, v8
	v_mul_f32_e32 v61, v39, v6
	v_or_b32_e32 v6, s88, v31
	v_lshlrev_b32_e32 v6, 7, v6
	v_mov_b32_e32 v7, v1
	v_lshl_add_u64 v[6:7], v[6:7], 2, s[40:41]
	v_lshl_add_u64 v[6:7], v[6:7], 0, v[20:21]
	v_and_b32_e32 v8, 0xffff0000, v8
	v_mul_f32_e32 v98, v8, v8
	v_fmamk_f32 v98, v98, 0xbdd2d3e7, v129
	v_mul_f32_e32 v98, v98, v8
	v_exp_f32_e32 v98, v98
	v_and_b32_e32 v99, 0xffff0000, v9
	v_and_b32_e32 v105, 0xffff0000, v5
	s_waitcnt vmcnt(4)
	v_fmac_f32_e32 v14, v15, v65
	v_mul_u32_u24_e32 v15, 0x110, v76
	v_cvt_pk_bf16_f32 v14, v14, s0
	v_add3_u32 v15, s15, v15, v33
	v_or_b32_e32 v65, 6, v34
	ds_write_b16 v15, v14 offset:34816
	v_lshlrev_b32_e32 v14, 2, v65
	global_load_dword v85, v14, s[16:17]
	global_load_dword v86, v14, s[20:21]
	s_waitcnt vmcnt(4)
	v_fmac_f32_e32 v17, v16, v59
	v_lshlrev_b32_e32 v14, 2, v78
	v_mul_u32_u24_e32 v15, 0x110, v77
	global_load_dword v87, v14, s[16:17]
	global_load_dword v88, v14, s[20:21]
	v_cvt_pk_bf16_f32 v14, v17, s0
	v_add3_u32 v15, s15, v15, v33
	ds_write_b16 v15, v14 offset:34816
	v_lshlrev_b32_e32 v14, 2, v81
	global_load_dwordx2 v[22:23], v20, s[16:17] offset:208
	global_load_dwordx2 v[24:25], v20, s[20:21] offset:208
	global_load_dword v89, v14, s[16:17]
	global_load_dword v90, v14, s[20:21]
	v_lshlrev_b32_e32 v14, 2, v79
	global_load_dword v92, v14, s[16:17]
	global_load_dword v93, v14, s[20:21]
	v_mul_f32_e32 v14, v91, v91
	v_fmamk_f32 v14, v14, 0xbdd2d3e7, v129
	v_mul_f32_e32 v14, v14, v91
	v_or_b32_e32 v59, 14, v34
	v_lshlrev_b32_e32 v15, 2, v59
	global_load_dword v94, v15, s[16:17]
	global_load_dword v95, v15, s[20:21]
	v_exp_f32_e32 v96, v14
	global_load_dwordx2 v[14:15], v20, s[16:17] offset:224
	global_load_dwordx2 v[16:17], v20, s[16:17] offset:240
	global_load_dwordx2 v[26:27], v20, s[20:21] offset:224
	s_nop 0
	global_load_dwordx2 v[20:21], v20, s[20:21] offset:240
	v_or_b32_e32 v40, 20, v34
	v_or_b32_e32 v41, 24, v34
	v_or_b32_e32 v42, 28, v34
	v_or_b32_e32 v43, 32, v34
	v_or_b32_e32 v48, 36, v34
	v_or_b32_e32 v49, 40, v34
	v_or_b32_e32 v51, 44, v34
	v_or_b32_e32 v60, 52, v34
	s_waitcnt vmcnt(16)
	v_fma_f32 v10, v10, v82, v12
	v_cvt_pk_bf16_f32 v12, v10, s0
	v_or_b32_e32 v10, 15, v34
	v_add_f32_e32 v82, 1.0, v96
	v_lshlrev_b32_e32 v96, 2, v10
	global_load_dword v97, v96, s[16:17]
	s_nop 0
	global_load_dword v96, v96, s[20:21]
	v_rcp_f32_e32 v82, v82
	ds_write_b16 v35, v12 offset:47600
	v_fmac_f32_e32 v13, v11, v83
	v_cvt_pk_bf16_f32 v11, v13, s0
	v_fma_f32 v12, v82, v91, -v19
	v_lshlrev_b32_e32 v91, 16, v9
	v_add_f32_e32 v82, 1.0, v98
	v_mul_f32_e32 v98, v91, v91
	v_fmamk_f32 v98, v98, 0xbdd2d3e7, v129
	v_mul_f32_e32 v98, v98, v91
	v_rcp_f32_e32 v82, v82
	v_exp_f32_e32 v98, v98
	v_mul_f32_e32 v12, v39, v12
	v_mul_u32_u24_e32 v13, 0x110, v81
	v_fma_f32 v8, v82, v8, -v19
	v_add_f32_e32 v82, 1.0, v98
	v_rcp_f32_e32 v82, v82
	v_mul_f32_e32 v100, v39, v8
	v_add3_u32 v13, s15, v13, v33
	v_mul_f32_e32 v9, v99, v99
	v_fma_f32 v8, v82, v91, -v19
	v_mul_u32_u24_e32 v82, 0x110, v65
	v_add3_u32 v82, s15, v82, v33
	v_fmamk_f32 v9, v9, 0xbdd2d3e7, v129
	v_mul_f32_e32 v9, v9, v99
	v_exp_f32_e32 v9, v9
	v_or_b32_e32 v91, 26, v34
	v_or_b32_e32 v29, 56, v34
	v_or_b32_e32 v28, 60, v34
	v_add_f32_e32 v9, 1.0, v9
	v_rcp_f32_e32 v98, v9
	v_mul_f32_e32 v9, v39, v8
	v_readlane_b32 s46, v251, 56
	v_readlane_b32 s47, v251, 57
	v_fma_f32 v8, v98, v99, -v19
	v_or_b32_e32 v98, 30, v34
	v_mul_f32_e32 v8, v39, v8
	v_readlane_b32 s48, v251, 58
	v_readlane_b32 s49, v251, 59
	s_waitcnt vmcnt(16)
	v_fmac_f32_e32 v86, v45, v85
	v_cvt_pk_bf16_f32 v45, v86, s0
	ds_write_b16 v82, v45 offset:34816
	v_mul_u32_u24_e32 v45, 0x110, v78
	s_waitcnt vmcnt(14)
	v_fmac_f32_e32 v88, v44, v87
	v_cvt_pk_bf16_f32 v44, v88, s0
	v_add3_u32 v45, s15, v45, v33
	ds_write_b16 v45, v44 offset:34816
	ds_write_b16 v35, v11 offset:47872
	s_waitcnt vmcnt(12)
	v_fma_f32 v11, v22, v12, v24
	s_waitcnt vmcnt(10)
	v_fmac_f32_e32 v90, v89, v47
	v_cvt_pk_bf16_f32 v12, v90, s0
	ds_write_b16 v13, v12 offset:34816
	s_waitcnt vmcnt(8)
	v_fmac_f32_e32 v93, v92, v46
	v_mul_u32_u24_e32 v13, 0x110, v79
	v_cvt_pk_bf16_f32 v12, v93, s0
	v_add3_u32 v13, s15, v13, v33
	v_cvt_pk_bf16_f32 v11, v11, s0
	ds_write_b16 v13, v12 offset:34816
	ds_write_b16 v35, v11 offset:48688
	v_lshlrev_b32_e32 v13, 16, v2
	v_mul_f32_e32 v22, v13, v13
	v_fmamk_f32 v22, v22, 0xbdd2d3e7, v129
	v_mul_f32_e32 v22, v22, v13
	v_exp_f32_e32 v22, v22
	v_fmac_f32_e32 v25, v100, v23
	v_cvt_pk_bf16_f32 v11, v25, s0
	s_waitcnt vmcnt(6)
	v_fmac_f32_e32 v95, v55, v94
	v_mul_u32_u24_e32 v12, 0x110, v59
	ds_write_b16 v35, v11 offset:48960
	v_cvt_pk_bf16_f32 v11, v95, s0
	v_add3_u32 v12, s15, v12, v33
	ds_write_b16 v12, v11 offset:34816
	v_add_f32_e32 v12, 1.0, v22
	v_rcp_f32_e32 v12, v12
	s_waitcnt vmcnt(0)
	v_fmac_f32_e32 v96, v54, v97
	v_mul_u32_u24_e32 v22, 0x110, v10
	v_cvt_pk_bf16_f32 v11, v96, s0
	v_add3_u32 v22, s15, v22, v33
	v_and_b32_e32 v2, 0xffff0000, v2
	ds_write_b16 v22, v11 offset:34816
	v_fma_f32 v11, v12, v13, -v19
	v_mul_f32_e32 v12, v2, v2
	v_lshlrev_b32_e32 v13, 16, v3
	v_fmamk_f32 v12, v12, 0xbdd2d3e7, v129
	v_mul_f32_e32 v22, v13, v13
	v_mul_f32_e32 v12, v12, v2
	v_fmamk_f32 v22, v22, 0xbdd2d3e7, v129
	v_mul_f32_e32 v22, v22, v13
	v_exp_f32_e32 v12, v12
	v_exp_f32_e32 v22, v22
	v_mul_f32_e32 v11, v39, v11
	v_add_f32_e32 v12, 1.0, v12
	v_fma_f32 v11, v14, v11, v26
	v_rcp_f32_e32 v12, v12
	v_add_f32_e32 v14, 1.0, v22
	v_rcp_f32_e32 v14, v14
	v_and_b32_e32 v3, 0xffff0000, v3
	v_fma_f32 v2, v12, v2, -v19
	v_mul_f32_e32 v12, v39, v2
	v_fma_f32 v2, v14, v13, -v19
	v_mul_f32_e32 v13, v3, v3
	v_fmamk_f32 v13, v13, 0xbdd2d3e7, v129
	v_mul_f32_e32 v13, v13, v3
	v_or_b32_e32 v86, 18, v34
	v_or_b32_e32 v87, 19, v34
	v_lshlrev_b32_e32 v14, 2, v86
	v_lshlrev_b32_e32 v22, 2, v87
	global_load_dword v26, v14, s[16:17]
	s_nop 0
	global_load_dword v14, v14, s[20:21]
	s_nop 0
	global_load_dword v54, v22, s[16:17]
	global_load_dword v55, v22, s[20:21]
	v_lshlrev_b32_e32 v22, 16, v4
	v_exp_f32_e32 v13, v13
	v_mul_f32_e32 v23, v22, v22
	v_fmamk_f32 v23, v23, 0xbdd2d3e7, v129
	v_mul_f32_e32 v23, v23, v22
	v_add_f32_e32 v13, 1.0, v13
	v_rcp_f32_e32 v13, v13
	v_exp_f32_e32 v23, v23
	v_or_b32_e32 v88, 22, v34
	v_lshlrev_b32_e32 v24, 2, v88
	v_fma_f32 v3, v13, v3, -v19
	v_add_f32_e32 v13, 1.0, v23
	global_load_dword v82, v24, s[16:17]
	global_load_dword v83, v24, s[20:21]
	v_or_b32_e32 v89, 23, v34
	v_rcp_f32_e32 v13, v13
	v_and_b32_e32 v4, 0xffff0000, v4
	v_lshlrev_b32_e32 v24, 2, v89
	v_mul_f32_e32 v23, v4, v4
	global_load_dword v84, v24, s[16:17]
	global_load_dword v85, v24, s[20:21]
	v_fmamk_f32 v23, v23, 0xbdd2d3e7, v129
	v_mul_f32_e32 v23, v23, v4
	v_fma_f32 v13, v13, v22, -v19
	v_lshlrev_b32_e32 v22, 2, v91
	global_load_dword v92, v22, s[16:17]
	global_load_dword v93, v22, s[20:21]
	v_or_b32_e32 v94, 27, v34
	v_exp_f32_e32 v23, v23
	v_lshlrev_b32_e32 v22, 2, v94
	global_load_dword v95, v22, s[16:17]
	global_load_dword v96, v22, s[20:21]
	v_lshlrev_b32_e32 v97, 16, v5
	v_lshlrev_b32_e32 v22, 2, v98
	global_load_dword v99, v22, s[16:17]
	global_load_dword v100, v22, s[20:21]
	v_mul_f32_e32 v22, 0x3d372713, v97
	v_mul_f32_e32 v90, v39, v13
	v_add_f32_e32 v13, 1.0, v23
	v_lshlrev_b32_e32 v23, 2, v101
	v_mul_f32_e32 v22, v22, v97
	global_load_dword v102, v23, s[16:17]
	global_load_dword v103, v23, s[20:21]
	v_fma_f32 v22, v22, v97, v97
	v_mul_f32_e32 v22, 0xbfcc422a, v22
	v_mul_f32_e32 v104, 0x3fb8aa3b, v22
	global_load_dwordx4 v[22:25], v[6:7], off offset:16
	global_load_dwordx4 v[44:47], v[6:7], off
	v_rcp_f32_e32 v13, v13
	v_exp_f32_e32 v104, v104
	v_mul_f32_e32 v5, v105, v105
	v_fmamk_f32 v5, v5, 0xbdd2d3e7, v129
	v_mul_f32_e32 v5, v5, v105
	v_fma_f32 v4, v13, v4, -v19
	v_add_f32_e32 v13, 1.0, v104
	v_rcp_f32_e32 v13, v13
	v_exp_f32_e32 v5, v5
	v_mul_f32_e32 v106, v39, v4
	v_cvt_pk_bf16_f32 v11, v11, s0
	v_fma_f32 v4, v13, v97, -v19
	v_add_f32_e32 v5, 1.0, v5
	v_rcp_f32_e32 v104, v5
	v_fmac_f32_e32 v27, v15, v12
	v_mul_f32_e32 v5, v39, v4
	v_fma_f32 v16, v16, v90, v20
	v_fma_f32 v4, v104, v105, -v19
	v_mul_u32_u24_e32 v19, 0x110, v88
	v_add3_u32 v19, s15, v19, v33
	v_cvt_pk_bf16_f32 v16, v16, s0
	v_fmac_f32_e32 v21, v106, v17
	v_mul_f32_e32 v2, v39, v2
	v_mul_f32_e32 v3, v39, v3
	v_mul_f32_e32 v4, v39, v4
	v_mul_u32_u24_e32 v17, 0x110, v91
	v_add3_u32 v17, s15, v17, v33
	v_readlane_b32 s56, v252, 2
	v_readlane_b32 s57, v252, 3
	v_readlane_b32 s58, v252, 4
	v_readlane_b32 s59, v252, 5
	s_waitcnt vmcnt(16)
	v_fmac_f32_e32 v14, v26, v53
	v_cvt_pk_bf16_f32 v13, v14, s0
	v_mul_u32_u24_e32 v14, 0x110, v86
	v_add3_u32 v14, s15, v14, v33
	ds_write_b16 v14, v13 offset:34816
	s_waitcnt vmcnt(14)
	v_fmac_f32_e32 v55, v54, v52
	v_mul_u32_u24_e32 v14, 0x110, v87
	v_cvt_pk_bf16_f32 v13, v55, s0
	v_add3_u32 v14, s15, v14, v33
	ds_write_b16 v14, v13 offset:34816
	ds_write_b16 v35, v11 offset:49776
	v_cvt_pk_bf16_f32 v11, v27, s0
	ds_write_b16 v35, v11 offset:50048
	global_load_dwordx4 v[12:15], v[6:7], off offset:48
	global_load_dwordx4 v[52:55], v[6:7], off offset:32
	s_waitcnt vmcnt(14)
	v_fmac_f32_e32 v83, v58, v82
	v_cvt_pk_bf16_f32 v11, v83, s0
	ds_write_b16 v19, v11 offset:34816
	v_mul_u32_u24_e32 v19, 0x110, v89
	v_add3_u32 v19, s15, v19, v33
	v_or_b32_e32 v58, 35, v34
	s_waitcnt vmcnt(12)
	v_fmac_f32_e32 v85, v56, v84
	v_cvt_pk_bf16_f32 v11, v85, s0
	v_or_b32_e32 v56, 34, v34
	ds_write_b16 v19, v11 offset:34816
	v_lshlrev_b32_e32 v11, 2, v56
	v_lshlrev_b32_e32 v19, 2, v58
	global_load_dword v39, v11, s[16:17]
	s_nop 0
	global_load_dword v11, v11, s[20:21]
	s_nop 0
	global_load_dword v90, v19, s[16:17]
	global_load_dword v97, v19, s[20:21]
	ds_write_b16 v35, v16 offset:50864
	v_cvt_pk_bf16_f32 v16, v21, s0
	s_waitcnt vmcnt(14)
	v_fmac_f32_e32 v93, v92, v64
	ds_write_b16 v35, v16 offset:51136
	v_cvt_pk_bf16_f32 v16, v93, s0
	ds_write_b16 v17, v16 offset:34816
	s_waitcnt vmcnt(12)
	v_fmac_f32_e32 v96, v95, v63
	v_mul_u32_u24_e32 v17, 0x110, v94
	v_cvt_pk_bf16_f32 v16, v96, s0
	v_add3_u32 v17, s15, v17, v33
	ds_write_b16 v17, v16 offset:34816
	s_waitcnt vmcnt(10)
	v_fmac_f32_e32 v100, v69, v99
	v_mul_u32_u24_e32 v17, 0x110, v98
	v_cvt_pk_bf16_f32 v16, v100, s0
	v_add3_u32 v17, s15, v17, v33
	ds_write_b16 v17, v16 offset:34816
	s_waitcnt vmcnt(8)
	v_fmac_f32_e32 v103, v68, v102
	v_mul_u32_u24_e32 v17, 0x110, v101
	v_cvt_pk_bf16_f32 v16, v103, s0
	v_add3_u32 v17, s15, v17, v33
	ds_write_b16 v17, v16 offset:34816
	s_waitcnt vmcnt(6)
	v_cndmask_b32_e32 v16, 0, v45, vcc
	v_cmp_le_u32_e32 vcc, v34, v31
	v_or_b32_e32 v35, 38, v34
	v_or_b32_e32 v68, 39, v34
	v_cndmask_b32_e32 v17, 0, v44, vcc
	v_cvt_pk_bf16_f32 v16, v17, v16
	v_lshlrev_b32_e32 v17, 2, v35
	global_load_dword v63, v17, s[16:17]
	global_load_dword v64, v17, s[20:21]
	v_lshlrev_b32_e32 v19, 2, v68
	global_load_dword v69, v19, s[16:17]
	global_load_dword v92, v19, s[20:21]
	v_cvt_pk_bf16_f32 v17, v46, v47
	v_cmp_le_u32_e32 vcc, v76, v31
	global_load_dwordx4 v[44:47], v[6:7], off offset:80
	global_load_dwordx4 v[82:85], v[6:7], off offset:64
	v_cndmask_b32_e32 v19, 0, v17, vcc
	v_lshrrev_b32_e32 v17, 16, v17
	v_cmp_le_u32_e32 vcc, v77, v31
	v_or_b32_e32 v77, 47, v34
	s_waitcnt vmcnt(8)
	v_fmac_f32_e32 v11, v39, v73
	v_cndmask_b32_e32 v17, 0, v17, vcc
	v_cmp_gt_u32_e32 vcc, v31, v18
	v_perm_b32 v17, v17, v19, s19
	v_cvt_pk_bf16_f32 v11, v11, s0
	v_cndmask_b32_e32 v19, 0, v23, vcc
	v_cmp_le_u32_e32 vcc, v18, v31
	s_waitcnt vmcnt(6)
	v_fmac_f32_e32 v97, v90, v72
	s_waitcnt vmcnt(4)
	v_fmac_f32_e32 v64, v71, v63
	v_cndmask_b32_e32 v18, 0, v22, vcc
	v_cvt_pk_bf16_f32 v18, v18, v19
	v_cvt_pk_bf16_f32 v19, v24, v25
	v_cmp_le_u32_e32 vcc, v65, v31
	s_waitcnt vmcnt(2)
	v_fmac_f32_e32 v92, v70, v69
	v_cndmask_b32_e32 v20, 0, v19, vcc
	v_lshrrev_b32_e32 v19, 16, v19
	v_cmp_le_u32_e32 vcc, v78, v31
	s_nop 1
	v_cndmask_b32_e32 v19, 0, v19, vcc
	v_perm_b32 v19, v19, v20, s19
	ds_write_b128 v0, v[16:19]
	global_load_dwordx4 v[20:23], v[6:7], off offset:112
	global_load_dwordx4 v[24:27], v[6:7], off offset:96
	v_cmp_gt_u32_e32 vcc, v31, v36
	s_nop 1
	v_cndmask_b32_e32 v16, 0, v53, vcc
	v_cmp_le_u32_e32 vcc, v36, v31
	s_nop 1
	v_cndmask_b32_e32 v17, 0, v52, vcc
	v_cvt_pk_bf16_f32 v16, v17, v16
	v_cvt_pk_bf16_f32 v17, v54, v55
	v_cmp_le_u32_e32 vcc, v81, v31
	v_or_b32_e32 v52, 42, v34
	v_or_b32_e32 v55, 43, v34
	v_cndmask_b32_e32 v18, 0, v17, vcc
	v_lshrrev_b32_e32 v17, 16, v17
	v_cmp_le_u32_e32 vcc, v79, v31
	v_lshlrev_b32_e32 v19, 2, v55
	v_and_or_b32 v81, v30, 64, v32
	v_cndmask_b32_e32 v17, 0, v17, vcc
	v_perm_b32 v17, v17, v18, s19
	v_mul_u32_u24_e32 v18, 0x110, v56
	v_add3_u32 v18, s15, v18, v33
	ds_write_b16 v18, v11 offset:34816
	v_lshlrev_b32_e32 v18, 2, v52
	global_load_dword v53, v18, s[16:17]
	global_load_dword v54, v18, s[20:21]
	v_mul_u32_u24_e32 v18, 0x110, v58
	v_cvt_pk_bf16_f32 v11, v97, s0
	v_add3_u32 v18, s15, v18, v33
	v_cmp_gt_u32_e32 vcc, v31, v37
	global_load_dword v65, v19, s[16:17]
	global_load_dword v72, v19, s[20:21]
	ds_write_b16 v18, v11 offset:34816
	v_cndmask_b32_e32 v11, 0, v13, vcc
	v_cmp_le_u32_e32 vcc, v37, v31
	s_waitcnt vmcnt(2)
	v_fmac_f32_e32 v54, v53, v67
	v_cndmask_b32_e32 v12, 0, v12, vcc
	v_cvt_pk_bf16_f32 v18, v12, v11
	v_cvt_pk_bf16_f32 v11, v14, v15
	v_cmp_le_u32_e32 vcc, v59, v31
	v_or_b32_e32 v59, 46, v34
	s_waitcnt vmcnt(0)
	v_fmac_f32_e32 v72, v65, v66
	v_cndmask_b32_e32 v12, 0, v11, vcc
	v_lshrrev_b32_e32 v11, 16, v11
	v_cmp_le_u32_e32 vcc, v10, v31
	s_nop 1
	v_cndmask_b32_e32 v10, 0, v11, vcc
	v_perm_b32 v19, v10, v12, s19
	v_lshlrev_b32_e32 v10, 2, v59
	global_load_dword v73, v10, s[16:17]
	global_load_dword v76, v10, s[20:21]
	ds_write_b128 v0, v[16:19] offset:16
	v_lshlrev_b32_e32 v10, 2, v77
	v_mul_u32_u24_e32 v11, 0x110, v35
	global_load_dword v78, v10, s[16:17]
	global_load_dword v79, v10, s[20:21]
	v_cvt_pk_bf16_f32 v10, v64, s0
	v_add3_u32 v11, s15, v11, v33
	ds_write_b16 v11, v10 offset:34816
	global_load_dwordx4 v[10:13], v[6:7], off offset:144
	global_load_dwordx4 v[14:17], v[6:7], off offset:128
	v_mul_u32_u24_e32 v19, 0x110, v68
	v_cvt_pk_bf16_f32 v18, v92, s0
	v_add3_u32 v19, s15, v19, v33
	v_cmp_gt_u32_e32 vcc, v31, v38
	ds_write_b16 v19, v18 offset:34816
	s_waitcnt vmcnt(4)
	v_fmac_f32_e32 v76, v75, v73
	v_cndmask_b32_e32 v18, 0, v83, vcc
	v_cmp_le_u32_e32 vcc, v38, v31
	s_waitcnt vmcnt(2)
	v_fmac_f32_e32 v79, v74, v78
	v_cndmask_b32_e32 v19, 0, v82, vcc
	v_cvt_pk_bf16_f32 v36, v19, v18
	v_cvt_pk_bf16_f32 v18, v84, v85
	v_cmp_le_u32_e32 vcc, v86, v31
	v_or_b32_e32 v82, s4, v81
	s_nop 0
	v_cndmask_b32_e32 v19, 0, v18, vcc
	v_lshrrev_b32_e32 v18, 16, v18
	v_cmp_le_u32_e32 vcc, v87, v31
	s_nop 1
	v_cndmask_b32_e32 v18, 0, v18, vcc
	v_cmp_gt_u32_e32 vcc, v31, v40
	v_perm_b32 v37, v18, v19, s19
	s_nop 0
	v_cndmask_b32_e32 v18, 0, v45, vcc
	v_cmp_le_u32_e32 vcc, v40, v31
	s_nop 1
	v_cndmask_b32_e32 v19, 0, v44, vcc
	v_cvt_pk_bf16_f32 v38, v19, v18
	v_cvt_pk_bf16_f32 v18, v46, v47
	v_cmp_le_u32_e32 vcc, v88, v31
	s_nop 1
	v_cndmask_b32_e32 v19, 0, v18, vcc
	v_lshrrev_b32_e32 v18, 16, v18
	v_cmp_le_u32_e32 vcc, v89, v31
	s_nop 1
	v_cndmask_b32_e32 v18, 0, v18, vcc
	v_cmp_gt_u32_e32 vcc, v31, v41
	v_perm_b32 v39, v18, v19, s19
	ds_write_b128 v0, v[36:39] offset:32
	v_cndmask_b32_e32 v18, 0, v25, vcc
	v_cmp_le_u32_e32 vcc, v41, v31
	v_mul_u32_u24_e32 v41, 0x110, v52
	v_add3_u32 v41, s15, v41, v33
	v_cndmask_b32_e32 v19, 0, v24, vcc
	v_cvt_pk_bf16_f32 v18, v19, v18
	v_cvt_pk_bf16_f32 v19, v26, v27
	global_load_dwordx4 v[24:27], v[6:7], off offset:176
	global_load_dwordx4 v[36:39], v[6:7], off offset:160
	v_cmp_le_u32_e32 vcc, v91, v31
	s_nop 1
	v_cndmask_b32_e32 v40, 0, v19, vcc
	v_lshrrev_b32_e32 v19, 16, v19
	v_cmp_le_u32_e32 vcc, v94, v31
	s_nop 1
	v_cndmask_b32_e32 v19, 0, v19, vcc
	v_cmp_gt_u32_e32 vcc, v31, v42
	v_perm_b32 v19, v19, v40, s19
	v_cvt_pk_bf16_f32 v40, v54, s0
	v_cndmask_b32_e32 v21, 0, v21, vcc
	v_cmp_le_u32_e32 vcc, v42, v31
	ds_write_b16 v41, v40 offset:34816
	v_mul_u32_u24_e32 v41, 0x110, v55
	v_cndmask_b32_e32 v20, 0, v20, vcc
	v_cvt_pk_bf16_f32 v20, v20, v21
	v_cvt_pk_bf16_f32 v21, v22, v23
	v_cmp_le_u32_e32 vcc, v98, v31
	v_cvt_pk_bf16_f32 v40, v72, s0
	v_add3_u32 v41, s15, v41, v33
	v_cndmask_b32_e32 v22, 0, v21, vcc
	v_lshrrev_b32_e32 v21, 16, v21
	v_cmp_le_u32_e32 vcc, v101, v31
	ds_write_b16 v41, v40 offset:34816
	v_mul_u32_u24_e32 v23, 0x110, v77
	v_cndmask_b32_e32 v21, 0, v21, vcc
	v_perm_b32 v21, v21, v22, s19
	ds_write_b128 v0, v[18:21] offset:48
	v_mul_u32_u24_e32 v19, 0x110, v59
	v_cvt_pk_bf16_f32 v18, v76, s0
	v_add3_u32 v19, s15, v19, v33
	v_cmp_gt_u32_e32 vcc, v31, v43
	ds_write_b16 v19, v18 offset:34816
	v_cvt_pk_bf16_f32 v22, v79, s0
	v_add3_u32 v23, s15, v23, v33
	s_waitcnt vmcnt(2)
	v_cndmask_b32_e32 v15, 0, v15, vcc
	v_cmp_le_u32_e32 vcc, v43, v31
	global_load_dwordx4 v[18:21], v[6:7], off offset:208
	global_load_dwordx4 v[44:47], v[6:7], off offset:192
	ds_write_b16 v23, v22 offset:34816
	v_cndmask_b32_e32 v14, 0, v14, vcc
	v_or_b32_e32 v23, 50, v34
	v_cvt_pk_bf16_f32 v14, v14, v15
	v_cvt_pk_bf16_f32 v15, v16, v17
	v_or_b32_e32 v22, 51, v34
	v_lshlrev_b32_e32 v17, 2, v23
	v_cmp_le_u32_e32 vcc, v56, v31
	global_load_dword v40, v17, s[16:17]
	global_load_dword v41, v17, s[20:21]
	v_lshlrev_b32_e32 v17, 2, v22
	v_cndmask_b32_e32 v16, 0, v15, vcc
	v_lshrrev_b32_e32 v15, 16, v15
	global_load_dword v42, v17, s[16:17]
	global_load_dword v43, v17, s[20:21]
	v_cmp_le_u32_e32 vcc, v58, v31
	s_waitcnt vmcnt(2)
	v_fmac_f32_e32 v41, v40, v62
	v_cndmask_b32_e32 v15, 0, v15, vcc
	v_cmp_gt_u32_e32 vcc, v31, v48
	v_perm_b32 v15, v15, v16, s19
	s_waitcnt vmcnt(0)
	v_fmac_f32_e32 v43, v42, v61
	v_cndmask_b32_e32 v11, 0, v11, vcc
	v_cmp_le_u32_e32 vcc, v48, v31
	v_or_b32_e32 v48, 54, v34
	s_nop 0
	v_cndmask_b32_e32 v10, 0, v10, vcc
	v_cvt_pk_bf16_f32 v16, v10, v11
	v_cvt_pk_bf16_f32 v10, v12, v13
	v_cmp_le_u32_e32 vcc, v35, v31
	v_or_b32_e32 v35, 55, v34
	s_nop 0
	v_cndmask_b32_e32 v11, 0, v10, vcc
	v_lshrrev_b32_e32 v10, 16, v10
	v_cmp_le_u32_e32 vcc, v68, v31
	s_nop 1
	v_cndmask_b32_e32 v10, 0, v10, vcc
	v_perm_b32 v17, v10, v11, s19
	v_lshlrev_b32_e32 v10, 2, v48
	global_load_dword v53, v10, s[16:17]
	global_load_dword v54, v10, s[20:21]
	v_lshlrev_b32_e32 v10, 2, v35
	global_load_dword v56, v10, s[16:17]
	global_load_dword v58, v10, s[20:21]
	v_cmp_gt_u32_e32 vcc, v31, v49
	ds_write_b128 v0, v[14:17] offset:64
	s_waitcnt vmcnt(2)
	v_fmac_f32_e32 v54, v9, v53
	v_cndmask_b32_e32 v10, 0, v37, vcc
	v_cmp_le_u32_e32 vcc, v49, v31
	v_or_b32_e32 v49, 59, v34
	v_cvt_pk_bf16_f32 v9, v54, s0
	v_cndmask_b32_e32 v11, 0, v36, vcc
	v_cvt_pk_bf16_f32 v10, v11, v10
	v_cvt_pk_bf16_f32 v11, v38, v39
	v_cmp_le_u32_e32 vcc, v52, v31
	global_load_dwordx4 v[14:17], v[6:7], off offset:240
	global_load_dwordx4 v[36:39], v[6:7], off offset:224
	v_cndmask_b32_e32 v12, 0, v11, vcc
	v_lshrrev_b32_e32 v11, 16, v11
	v_cmp_le_u32_e32 vcc, v55, v31
	v_or_b32_e32 v52, 58, v34
	s_waitcnt vmcnt(2)
	v_fmac_f32_e32 v58, v8, v56
	v_cndmask_b32_e32 v6, 0, v11, vcc
	v_perm_b32 v11, v6, v12, s19
	v_lshlrev_b32_e32 v6, 2, v52
	global_load_dword v55, v6, s[16:17]
	global_load_dword v63, v6, s[20:21]
	v_lshlrev_b32_e32 v6, 2, v49
	v_cmp_gt_u32_e32 vcc, v31, v51
	global_load_dword v64, v6, s[16:17]
	global_load_dword v65, v6, s[20:21]
	v_cndmask_b32_e32 v6, 0, v25, vcc
	v_cmp_le_u32_e32 vcc, v51, v31
	s_waitcnt vmcnt(2)
	v_fmac_f32_e32 v63, v55, v2
	v_cndmask_b32_e32 v7, 0, v24, vcc
	v_cvt_pk_bf16_f32 v12, v7, v6
	v_cvt_pk_bf16_f32 v6, v26, v27
	v_cmp_le_u32_e32 vcc, v59, v31
	v_mul_u32_u24_e32 v26, 0x110, v22
	v_cvt_pk_bf16_f32 v27, v41, s0
	v_cndmask_b32_e32 v7, 0, v6, vcc
	v_lshrrev_b32_e32 v6, 16, v6
	v_cmp_le_u32_e32 vcc, v77, v31
	v_add3_u32 v26, s15, v26, v33
	v_cvt_pk_bf16_f32 v2, v63, s0
	v_cndmask_b32_e32 v6, 0, v6, vcc
	v_perm_b32 v13, v6, v7, s19
	ds_write_b128 v0, v[10:13] offset:80
	v_or_b32_e32 v11, 62, v34
	v_or_b32_e32 v10, 63, v34
	v_lshlrev_b32_e32 v7, 2, v11
	global_load_dword v12, v7, s[16:17]
	global_load_dword v13, v7, s[20:21]
	v_lshlrev_b32_e32 v7, 2, v10
	global_load_dword v24, v7, s[16:17]
	global_load_dword v25, v7, s[20:21]
	v_cmp_gt_u32_e32 vcc, v31, v57
	s_waitcnt vmcnt(4)
	v_fmac_f32_e32 v65, v64, v3
	s_waitcnt vmcnt(2)
	v_fmac_f32_e32 v13, v5, v12
	v_cndmask_b32_e32 v6, 0, v45, vcc
	v_cmp_le_u32_e32 vcc, v57, v31
	v_cvt_pk_bf16_f32 v5, v13, s0
	s_waitcnt vmcnt(0)
	v_fmac_f32_e32 v25, v4, v24
	v_cndmask_b32_e32 v7, 0, v44, vcc
	v_cvt_pk_bf16_f32 v6, v7, v6
	v_mul_u32_u24_e32 v7, 0x110, v23
	v_add3_u32 v7, s15, v7, v33
	ds_write_b16 v7, v27 offset:34816
	v_cvt_pk_bf16_f32 v7, v43, s0
	ds_write_b16 v26, v7 offset:34816
	v_cvt_pk_bf16_f32 v7, v46, v47
	v_cmp_le_u32_e32 vcc, v23, v31
	s_nop 1
	v_cndmask_b32_e32 v23, 0, v7, vcc
	v_lshrrev_b32_e32 v7, 16, v7
	v_cmp_le_u32_e32 vcc, v22, v31
	s_nop 1
	v_cndmask_b32_e32 v7, 0, v7, vcc
	v_perm_b32 v7, v7, v23, s19
	v_cmp_gt_u32_e32 vcc, v31, v60
	ds_write_b64 v0, v[6:7] offset:96
	s_nop 0
	v_cndmask_b32_e32 v6, 0, v19, vcc
	v_cmp_le_u32_e32 vcc, v60, v31
	s_nop 1
	v_cndmask_b32_e32 v7, 0, v18, vcc
	v_cvt_pk_bf16_f32 v6, v7, v6
	v_mul_u32_u24_e32 v7, 0x110, v48
	v_add3_u32 v7, s15, v7, v33
	v_mul_u32_u24_e32 v18, 0x110, v35
	v_add3_u32 v18, s15, v18, v33
	ds_write_b16 v7, v9 offset:34816
	v_cvt_pk_bf16_f32 v7, v58, s0
	ds_write_b16 v18, v7 offset:34816
	v_cvt_pk_bf16_f32 v7, v20, v21
	v_cmp_le_u32_e32 vcc, v48, v31
	s_nop 1
	v_cndmask_b32_e32 v8, 0, v7, vcc
	v_lshrrev_b32_e32 v7, 16, v7
	v_cmp_le_u32_e32 vcc, v35, v31
	s_nop 1
	v_cndmask_b32_e32 v7, 0, v7, vcc
	v_perm_b32 v7, v7, v8, s19
	v_cmp_gt_u32_e32 vcc, v31, v29
	ds_write_b64 v0, v[6:7] offset:104
	v_mul_u32_u24_e32 v8, 0x110, v49
	v_cndmask_b32_e32 v6, 0, v37, vcc
	v_cmp_le_u32_e32 vcc, v29, v31
	v_add3_u32 v8, s15, v8, v33
	s_nop 0
	v_cndmask_b32_e32 v7, 0, v36, vcc
	v_cvt_pk_bf16_f32 v6, v7, v6
	v_mul_u32_u24_e32 v7, 0x110, v52
	v_add3_u32 v7, s15, v7, v33
	ds_write_b16 v7, v2 offset:34816
	v_cvt_pk_bf16_f32 v2, v65, s0
	ds_write_b16 v8, v2 offset:34816
	v_cvt_pk_bf16_f32 v2, v38, v39
	v_cmp_le_u32_e32 vcc, v52, v31
	s_nop 1
	v_cndmask_b32_e32 v3, 0, v2, vcc
	v_lshrrev_b32_e32 v2, 16, v2
	v_cmp_le_u32_e32 vcc, v49, v31
	s_nop 1
	v_cndmask_b32_e32 v2, 0, v2, vcc
	v_cmp_gt_u32_e32 vcc, v31, v28
	v_perm_b32 v7, v2, v3, s19
	ds_write_b64 v0, v[6:7] offset:112
	v_cndmask_b32_e32 v2, 0, v15, vcc
	v_cmp_le_u32_e32 vcc, v28, v31
	v_mul_u32_u24_e32 v6, 0x110, v10
	v_add3_u32 v6, s15, v6, v33
	v_cndmask_b32_e32 v3, 0, v14, vcc
	v_cvt_pk_bf16_f32 v2, v3, v2
	v_mul_u32_u24_e32 v3, 0x110, v11
	v_add3_u32 v3, s15, v3, v33
	ds_write_b16 v3, v5 offset:34816
	v_cvt_pk_bf16_f32 v3, v25, s0
	ds_write_b16 v6, v3 offset:34816
	v_cvt_pk_bf16_f32 v3, v16, v17
	v_cmp_le_u32_e32 vcc, v11, v31
	v_mul_u32_u24_e32 v7, 0x88, v81
	v_lshlrev_b32_e32 v81, 2, v81
	v_cndmask_b32_e32 v4, 0, v3, vcc
	v_lshrrev_b32_e32 v3, 16, v3
	v_cmp_le_u32_e32 vcc, v10, v31
	s_nop 1
	v_cndmask_b32_e32 v3, 0, v3, vcc
	v_perm_b32 v3, v3, v4, s19
	ds_write_b64 v0, v[2:3] offset:120
	v_bfe_u32 v0, v50, 4, 2
	v_and_b32_e32 v2, 0x4f, v50
	v_lshl_add_u32 v6, v0, 4, s15
	v_mul_u32_u24_e32 v2, 0x88, v2
	v_lshl_add_u32 v51, v2, 1, v6
	s_waitcnt lgkmcnt(0)
	s_barrier
	ds_read_b128 v[2:5], v51 offset:34816
	ds_read_b128 v[72:75], v51 offset:34880
	ds_read_b128 v[14:17], v51 offset:39168
	ds_read_b128 v[76:79], v51 offset:39232
	ds_read_b128 v[22:25], v51 offset:43520
	ds_read_b128 v[84:87], v51 offset:43584
	ds_read_b128 v[30:33], v51 offset:47872
	ds_read_b128 v[88:91], v51 offset:47936
	v_lshl_add_u32 v83, v7, 1, v6
	ds_read_b128 v[6:9], v83
	ds_read_b128 v[34:37], v83 offset:4352
	ds_read_b128 v[52:55], v83 offset:8704
	ds_read_b128 v[68:71], v83 offset:13056
	s_waitcnt lgkmcnt(3)
	v_mfma_f32_16x16x32_bf16 v[10:13], v[2:5], v[6:9], 0
	ds_read_b128 v[100:103], v51 offset:48000
	v_and_b32_e32 v50, 64, v50
	v_mfma_f32_16x16x32_bf16 v[18:21], v[14:17], v[6:9], 0
	v_mfma_f32_16x16x32_bf16 v[26:29], v[22:25], v[6:9], 0
	v_mfma_f32_16x16x32_bf16 v[6:9], v[30:33], v[6:9], 0
	s_waitcnt lgkmcnt(3)
	v_mfma_f32_16x16x32_bf16 v[38:41], v[2:5], v[34:37], 0
	v_mfma_f32_16x16x32_bf16 v[42:45], v[14:17], v[34:37], 0
	v_mfma_f32_16x16x32_bf16 v[46:49], v[22:25], v[34:37], 0
	v_mfma_f32_16x16x32_bf16 v[34:37], v[30:33], v[34:37], 0
	s_waitcnt lgkmcnt(2)
	v_mfma_f32_16x16x32_bf16 v[56:59], v[2:5], v[52:55], 0
	v_mfma_f32_16x16x32_bf16 v[60:63], v[14:17], v[52:55], 0
	v_mfma_f32_16x16x32_bf16 v[64:67], v[22:25], v[52:55], 0
	v_mfma_f32_16x16x32_bf16 v[52:55], v[30:33], v[52:55], 0
	s_waitcnt lgkmcnt(1)
	v_mfma_f32_16x16x32_bf16 v[2:5], v[2:5], v[68:71], 0
	v_mfma_f32_16x16x32_bf16 v[14:17], v[14:17], v[68:71], 0
	v_mfma_f32_16x16x32_bf16 v[22:25], v[22:25], v[68:71], 0
	v_mfma_f32_16x16x32_bf16 v[30:33], v[30:33], v[68:71], 0
	ds_read_b128 v[68:71], v83 offset:64
	s_waitcnt lgkmcnt(0)
	v_mfma_f32_16x16x32_bf16 v[10:13], v[72:75], v[68:71], v[10:13]
	v_mfma_f32_16x16x32_bf16 v[18:21], v[76:79], v[68:71], v[18:21]
	v_mfma_f32_16x16x32_bf16 v[26:29], v[84:87], v[68:71], v[26:29]
	v_mfma_f32_16x16x32_bf16 v[6:9], v[88:91], v[68:71], v[6:9]
	ds_read_b128 v[68:71], v83 offset:4416
	s_waitcnt lgkmcnt(0)
	v_mfma_f32_16x16x32_bf16 v[38:41], v[72:75], v[68:71], v[38:41]
	v_mfma_f32_16x16x32_bf16 v[42:45], v[76:79], v[68:71], v[42:45]
	v_mfma_f32_16x16x32_bf16 v[46:49], v[84:87], v[68:71], v[46:49]
	v_mfma_f32_16x16x32_bf16 v[34:37], v[88:91], v[68:71], v[34:37]
	ds_read_b128 v[68:71], v83 offset:8768
	s_waitcnt lgkmcnt(0)
	v_mfma_f32_16x16x32_bf16 v[92:95], v[76:79], v[68:71], v[60:63]
	s_nop 2
	ds_read_b128 v[60:63], v83 offset:13120
	v_mfma_f32_16x16x32_bf16 v[56:59], v[72:75], v[68:71], v[56:59]
	v_mfma_f32_16x16x32_bf16 v[96:99], v[84:87], v[68:71], v[64:67]
	v_mfma_f32_16x16x32_bf16 v[52:55], v[88:91], v[68:71], v[52:55]
	s_nop 1
	ds_read_b128 v[66:69], v51 offset:34944
	s_waitcnt lgkmcnt(1)
	v_mfma_f32_16x16x32_bf16 v[2:5], v[72:75], v[60:63], v[2:5]
	v_mfma_f32_16x16x32_bf16 v[70:73], v[88:91], v[60:63], v[30:33]
	s_nop 2
	ds_read_b128 v[30:33], v83 offset:128
	v_mfma_f32_16x16x32_bf16 v[14:17], v[76:79], v[60:63], v[14:17]
	s_waitcnt lgkmcnt(0)
	v_mfma_f32_16x16x32_bf16 v[74:77], v[66:69], v[30:33], v[10:13]
	s_nop 2
	ds_read_b128 v[10:13], v51 offset:39296
	v_mfma_f32_16x16x32_bf16 v[22:25], v[84:87], v[60:63], v[22:25]
	v_mfma_f32_16x16x32_bf16 v[104:107], v[100:103], v[30:33], v[6:9]
	s_nop 2
	ds_read_b128 v[6:9], v83 offset:4480
	s_waitcnt lgkmcnt(1)
	v_mfma_f32_16x16x32_bf16 v[84:87], v[10:13], v[30:33], v[18:21]
	s_nop 2
	ds_read_b128 v[18:21], v51 offset:43648
	s_waitcnt lgkmcnt(1)
	v_mfma_f32_16x16x32_bf16 v[108:111], v[66:69], v[6:9], v[38:41]
	v_mfma_f32_16x16x32_bf16 v[112:115], v[10:13], v[6:9], v[42:45]
	s_waitcnt lgkmcnt(0)
	v_mfma_f32_16x16x32_bf16 v[116:119], v[18:21], v[6:9], v[46:49]
	v_mfma_f32_16x16x32_bf16 v[62:65], v[100:103], v[6:9], v[34:37]
	ds_read_b128 v[6:9], v83 offset:8832
	s_waitcnt lgkmcnt(0)
	v_mfma_f32_16x16x32_bf16 v[42:45], v[100:103], v[6:9], v[52:55]
	s_nop 2
	ds_read_b128 v[52:55], v83 offset:13184
	v_mfma_f32_16x16x32_bf16 v[88:91], v[18:21], v[30:33], v[26:29]
	ds_read_b128 v[30:33], v51 offset:35008
	v_mfma_f32_16x16x32_bf16 v[46:49], v[18:21], v[6:9], v[96:99]
	s_waitcnt lgkmcnt(1)
	v_mfma_f32_16x16x32_bf16 v[26:29], v[66:69], v[52:55], v[2:5]
	v_mfma_f32_16x16x32_bf16 v[2:5], v[18:21], v[52:55], v[22:25]
	ds_read_b128 v[18:21], v51 offset:39360
	v_mfma_f32_16x16x32_bf16 v[38:41], v[66:69], v[6:9], v[56:59]
	v_mfma_f32_16x16x32_bf16 v[34:37], v[10:13], v[6:9], v[92:95]
	v_mfma_f32_16x16x32_bf16 v[6:9], v[10:13], v[52:55], v[14:17]
	v_mfma_f32_16x16x32_bf16 v[10:13], v[100:103], v[52:55], v[70:73]
	ds_read_b128 v[52:55], v83 offset:192
	ds_read_b128 v[22:25], v51 offset:43712
	ds_read_b128 v[14:17], v51 offset:48064
	v_lshlrev_b32_e32 v70, 3, v0
	v_lshlrev_b32_e32 v0, 1, v50
	v_lshl_add_u64 v[50:51], s[6:7], 0, v[0:1]
	v_mov_b32_e32 v71, v1
	s_waitcnt lgkmcnt(2)
	v_mfma_f32_16x16x32_bf16 v[92:95], v[30:33], v[52:55], v[74:77]
	ds_read_b128 v[100:103], v83 offset:4544
	s_nop 1
	v_lshl_add_u64 v[74:75], v[50:51], 0, v[70:71]
	v_mad_u64_u32 v[72:73], s[0:1], v82, s3, v[74:75]
	v_mfma_f32_16x16x32_bf16 v[96:99], v[18:21], v[52:55], v[84:87]
	s_lshl_b64 s[0:1], s[88:89], 2
	s_add_u32 s12, s42, s0
	s_addc_u32 s13, s43, s1
	s_waitcnt lgkmcnt(2)
	v_mfma_f32_16x16x32_bf16 v[86:89], v[22:25], v[52:55], v[88:91]
	global_load_dword v85, v81, s[12:13]
	v_or_b32_e32 v84, 16, v82
	v_mad_u64_u32 v[78:79], s[0:1], v84, s3, v[74:75]
	global_load_dwordx2 v[90:91], v[72:73], off
	s_waitcnt lgkmcnt(1)
	v_mfma_f32_16x16x32_bf16 v[66:69], v[14:17], v[52:55], v[104:107]
	s_cmpk_gt_u32 s10, 0xff
	s_waitcnt vmcnt(1)
	v_add_f32_e32 v87, v87, v85
	global_load_dwordx2 v[104:105], v[72:73], off offset:32
	s_waitcnt lgkmcnt(0)
	v_mfma_f32_16x16x32_bf16 v[58:61], v[30:33], v[100:103], v[108:111]
	global_load_dwordx2 v[106:107], v[72:73], off offset:64
	s_nop 1
	global_load_dwordx2 v[108:109], v[72:73], off offset:96
	s_waitcnt vmcnt(3)
	v_lshlrev_b32_e32 v72, 16, v90
	v_mul_f32_e32 v73, v72, v72
	v_and_b32_e32 v90, 0xffff0000, v90
	v_fmamk_f32 v73, v73, 0xbdd2d3e7, v129
	v_mul_f32_e32 v76, v90, v90
	v_mul_f32_e32 v73, v73, v72
	v_fmamk_f32 v76, v76, 0xbdd2d3e7, v129
	v_mul_f32_e32 v76, v76, v90
	v_exp_f32_e32 v73, v73
	v_exp_f32_e32 v110, v76
	v_add_f32_e32 v86, v86, v85
	v_add_f32_e32 v73, 1.0, v73
	v_rcp_f32_e32 v73, v73
	v_add_f32_e32 v110, 1.0, v110
	v_rcp_f32_e32 v110, v110
	v_add_f32_e32 v88, v88, v85
	v_mul_f32_e32 v72, v73, v72
	v_add_f32_e32 v73, v92, v85
	v_mul_f32_e32 v72, v72, v73
	v_mul_f32_e32 v73, v110, v90
	v_add_f32_e32 v90, v93, v85
	v_lshlrev_b32_e32 v92, 16, v91
	v_mul_f32_e32 v73, v73, v90
	v_mul_f32_e32 v90, v92, v92
	v_and_b32_e32 v91, 0xffff0000, v91
	v_fmamk_f32 v90, v90, 0xbdd2d3e7, v129
	v_mul_f32_e32 v93, v91, v91
	v_mul_f32_e32 v90, v90, v92
	v_fmamk_f32 v93, v93, 0xbdd2d3e7, v129
	v_mul_f32_e32 v93, v93, v91
	v_exp_f32_e32 v90, v90
	v_exp_f32_e32 v93, v93
	v_add_f32_e32 v89, v89, v85
	v_add_f32_e32 v90, 1.0, v90
	v_rcp_f32_e32 v110, v90
	v_cvt_pk_bf16_f32 v90, v72, v73
	v_add_f32_e32 v72, 1.0, v93
	v_rcp_f32_e32 v72, v72
	v_mul_f32_e32 v73, v110, v92
	v_add_f32_e32 v92, v94, v85
	v_mul_f32_e32 v73, v73, v92
	v_mul_f32_e32 v72, v72, v91
	v_add_f32_e32 v91, v95, v85
	v_mul_f32_e32 v72, v72, v91
	v_cvt_pk_bf16_f32 v91, v73, v72
	v_mov_b64_e32 v[72:73], s[50:51]
	v_mad_u64_u32 v[92:93], s[0:1], v82, s3, v[72:73]
	v_lshl_add_u64 v[92:93], v[92:93], 0, s[8:9]
	v_lshl_add_u64 v[92:93], v[92:93], 0, v[0:1]
	v_lshl_add_u64 v[92:93], v[92:93], 0, v[70:71]
	global_store_dwordx2 v[92:93], v[90:91], off
	v_add_f32_e32 v67, v67, v85
	v_add_f32_e32 v66, v66, v85
	global_load_dwordx2 v[76:77], v[78:79], off
	v_add_f32_e32 v68, v68, v85
	v_add_f32_e32 v69, v69, v85
	v_mfma_f32_16x16x32_bf16 v[54:57], v[18:21], v[100:103], v[112:115]
	s_waitcnt vmcnt(4)
	v_lshlrev_b32_e32 v94, 16, v104
	v_mul_f32_e32 v95, v94, v94
	v_and_b32_e32 v104, 0xffff0000, v104
	v_fmamk_f32 v95, v95, 0xbdd2d3e7, v129
	v_mul_f32_e32 v110, v104, v104
	v_mul_f32_e32 v95, v95, v94
	v_fmamk_f32 v110, v110, 0xbdd2d3e7, v129
	v_mul_f32_e32 v110, v110, v104
	v_exp_f32_e32 v95, v95
	v_exp_f32_e32 v110, v110
	v_mfma_f32_16x16x32_bf16 v[50:53], v[22:25], v[100:103], v[116:119]
	v_add_f32_e32 v95, 1.0, v95
	v_rcp_f32_e32 v95, v95
	v_add_f32_e32 v90, 1.0, v110
	v_rcp_f32_e32 v90, v90
	v_mfma_f32_16x16x32_bf16 v[62:65], v[14:17], v[100:103], v[62:65]
	v_mul_f32_e32 v91, v95, v94
	v_add_f32_e32 v94, v96, v85
	v_mul_f32_e32 v91, v91, v94
	v_mul_f32_e32 v90, v90, v104
	v_add_f32_e32 v94, v97, v85
	v_mul_f32_e32 v90, v90, v94
	v_lshlrev_b32_e32 v94, 16, v105
	v_mul_f32_e32 v95, v94, v94
	v_and_b32_e32 v96, 0xffff0000, v105
	v_fmamk_f32 v95, v95, 0xbdd2d3e7, v129
	v_mul_f32_e32 v97, v96, v96
	v_mul_f32_e32 v95, v95, v94
	v_fmamk_f32 v97, v97, 0xbdd2d3e7, v129
	v_mul_f32_e32 v97, v97, v96
	v_exp_f32_e32 v95, v95
	v_exp_f32_e32 v97, v97
	v_cvt_pk_bf16_f32 v90, v91, v90
	v_add_f32_e32 v95, 1.0, v95
	v_rcp_f32_e32 v95, v95
	v_add_f32_e32 v91, 1.0, v97
	v_rcp_f32_e32 v91, v91
	v_mul_f32_e32 v94, v95, v94
	v_add_f32_e32 v95, v98, v85
	v_mul_f32_e32 v94, v94, v95
	v_mul_f32_e32 v91, v91, v96
	v_add_f32_e32 v95, v99, v85
	v_mul_f32_e32 v91, v91, v95
	s_waitcnt vmcnt(3)
	v_and_b32_e32 v96, 0xffff0000, v106
	v_cvt_pk_bf16_f32 v91, v94, v91
	v_lshlrev_b32_e32 v94, 16, v106
	v_mul_f32_e32 v97, v96, v96
	v_mul_f32_e32 v95, v94, v94
	v_fmamk_f32 v97, v97, 0xbdd2d3e7, v129
	v_fmamk_f32 v95, v95, 0xbdd2d3e7, v129
	v_mul_f32_e32 v97, v97, v96
	v_mul_f32_e32 v95, v95, v94
	v_exp_f32_e32 v97, v97
	v_exp_f32_e32 v95, v95
	global_store_dwordx2 v[92:93], v[90:91], off offset:32
	v_add_f32_e32 v90, 1.0, v97
	v_add_f32_e32 v95, 1.0, v95
	v_rcp_f32_e32 v90, v90
	v_rcp_f32_e32 v95, v95
	v_mul_f32_e32 v90, v90, v96
	v_mul_f32_e32 v91, v95, v94
	v_mul_f32_e32 v87, v90, v87
	v_lshlrev_b32_e32 v90, 16, v107
	v_and_b32_e32 v94, 0xffff0000, v107
	v_mul_f32_e32 v86, v91, v86
	v_mul_f32_e32 v91, v90, v90
	v_mul_f32_e32 v95, v94, v94
	v_fmamk_f32 v91, v91, 0xbdd2d3e7, v129
	v_fmamk_f32 v95, v95, 0xbdd2d3e7, v129
	v_mul_f32_e32 v91, v91, v90
	v_mul_f32_e32 v95, v95, v94
	v_exp_f32_e32 v91, v91
	v_exp_f32_e32 v95, v95
	v_cvt_pk_bf16_f32 v86, v86, v87
	v_add_f32_e32 v91, 1.0, v91
	v_add_f32_e32 v87, 1.0, v95
	v_rcp_f32_e32 v91, v91
	v_rcp_f32_e32 v87, v87
	v_mul_f32_e32 v90, v91, v90
	v_mul_f32_e32 v87, v87, v94
	v_mul_f32_e32 v88, v90, v88
	v_mul_f32_e32 v87, v87, v89
	s_waitcnt vmcnt(3)
	v_and_b32_e32 v90, 0xffff0000, v108
	v_cvt_pk_bf16_f32 v87, v88, v87
	v_lshlrev_b32_e32 v88, 16, v108
	v_mul_f32_e32 v91, v90, v90
	v_mul_f32_e32 v89, v88, v88
	v_fmamk_f32 v91, v91, 0xbdd2d3e7, v129
	v_fmamk_f32 v89, v89, 0xbdd2d3e7, v129
	v_mul_f32_e32 v91, v91, v90
	v_mul_f32_e32 v89, v89, v88
	v_exp_f32_e32 v91, v91
	v_exp_f32_e32 v89, v89
	global_store_dwordx2 v[92:93], v[86:87], off offset:64
	v_add_f32_e32 v86, 1.0, v91
	v_add_f32_e32 v89, 1.0, v89
	v_rcp_f32_e32 v86, v86
	v_rcp_f32_e32 v89, v89
	v_mul_f32_e32 v86, v86, v90
	v_mul_f32_e32 v87, v89, v88
	v_mul_f32_e32 v67, v86, v67
	v_lshlrev_b32_e32 v86, 16, v109
	v_and_b32_e32 v88, 0xffff0000, v109
	v_mul_f32_e32 v66, v87, v66
	v_mul_f32_e32 v87, v86, v86
	v_mul_f32_e32 v89, v88, v88
	v_fmamk_f32 v87, v87, 0xbdd2d3e7, v129
	v_fmamk_f32 v89, v89, 0xbdd2d3e7, v129
	v_mul_f32_e32 v87, v87, v86
	v_mul_f32_e32 v89, v89, v88
	v_exp_f32_e32 v87, v87
	v_exp_f32_e32 v89, v89
	v_cvt_pk_bf16_f32 v66, v66, v67
	global_load_dwordx2 v[90:91], v[78:79], off offset:32
	v_add_f32_e32 v87, 1.0, v87
	v_add_f32_e32 v67, 1.0, v89
	v_rcp_f32_e32 v87, v87
	v_rcp_f32_e32 v67, v67
	v_mul_f32_e32 v86, v87, v86
	v_mul_f32_e32 v67, v67, v88
	v_mul_f32_e32 v68, v68, v86
	v_mul_f32_e32 v67, v69, v67
	v_cvt_pk_bf16_f32 v67, v68, v67
	global_store_dwordx2 v[92:93], v[66:67], off offset:96
	global_load_dword v85, v81, s[12:13] offset:64
	ds_read_b128 v[86:89], v83 offset:8896
	global_load_dwordx2 v[92:93], v[78:79], off offset:64
	global_load_dwordx2 v[94:95], v[78:79], off offset:96
	s_waitcnt vmcnt(7)
	v_lshlrev_b32_e32 v79, 16, v76
	v_and_b32_e32 v76, 0xffff0000, v76
	v_mul_f32_e32 v67, v76, v76
	v_mul_f32_e32 v66, v79, v79
	v_fmamk_f32 v67, v67, 0xbdd2d3e7, v129
	v_fmamk_f32 v66, v66, 0xbdd2d3e7, v129
	v_mul_f32_e32 v67, v67, v76
	v_mul_f32_e32 v66, v66, v79
	v_exp_f32_e32 v96, v67
	v_exp_f32_e32 v66, v66
	v_or_b32_e32 v78, 32, v82
	v_mad_u64_u32 v[68:69], s[0:1], v78, s3, v[74:75]
	v_add_f32_e32 v96, 1.0, v96
	v_add_f32_e32 v66, 1.0, v66
	v_rcp_f32_e32 v96, v96
	v_rcp_f32_e32 v97, v66
	global_load_dwordx2 v[66:67], v[68:69], off
	s_waitcnt lgkmcnt(0)
	v_mfma_f32_16x16x32_bf16 v[38:41], v[30:33], v[86:89], v[38:41]
	v_mul_f32_e32 v76, v96, v76
	v_mul_f32_e32 v79, v97, v79
	s_waitcnt vmcnt(3)
	v_add_f32_e32 v59, v59, v85
	v_add_f32_e32 v58, v58, v85
	v_mul_f32_e32 v59, v76, v59
	v_lshlrev_b32_e32 v76, 16, v77
	v_and_b32_e32 v77, 0xffff0000, v77
	v_mul_f32_e32 v58, v79, v58
	v_mul_f32_e32 v79, v76, v76
	v_mul_f32_e32 v96, v77, v77
	v_fmamk_f32 v79, v79, 0xbdd2d3e7, v129
	v_fmamk_f32 v96, v96, 0xbdd2d3e7, v129
	v_mul_f32_e32 v79, v79, v76
	v_mul_f32_e32 v96, v96, v77
	v_exp_f32_e32 v79, v79
	v_exp_f32_e32 v96, v96
	v_cvt_pk_bf16_f32 v58, v58, v59
	v_add_f32_e32 v60, v60, v85
	v_add_f32_e32 v79, 1.0, v79
	v_add_f32_e32 v59, 1.0, v96
	v_rcp_f32_e32 v79, v79
	v_rcp_f32_e32 v59, v59
	v_add_f32_e32 v61, v61, v85
	v_add_f32_e32 v55, v55, v85
	v_mul_f32_e32 v76, v79, v76
	v_mul_f32_e32 v59, v59, v77
	v_mul_f32_e32 v60, v76, v60
	v_mul_f32_e32 v59, v59, v61
	v_and_b32_e32 v79, 0xffff0000, v90
	v_cvt_pk_bf16_f32 v59, v60, v59
	v_mad_u64_u32 v[60:61], s[0:1], v84, s3, v[72:73]
	v_lshlrev_b32_e32 v76, 16, v90
	v_mul_f32_e32 v84, v79, v79
	v_mul_f32_e32 v77, v76, v76
	v_fmamk_f32 v84, v84, 0xbdd2d3e7, v129
	v_fmamk_f32 v77, v77, 0xbdd2d3e7, v129
	v_mul_f32_e32 v84, v84, v79
	v_mul_f32_e32 v77, v77, v76
	v_exp_f32_e32 v84, v84
	v_lshl_add_u64 v[60:61], v[60:61], 0, s[8:9]
	v_exp_f32_e32 v77, v77
	v_lshl_add_u64 v[60:61], v[60:61], 0, v[0:1]
	v_lshl_add_u64 v[60:61], v[60:61], 0, v[70:71]
	global_store_dwordx2 v[60:61], v[58:59], off
	v_add_f32_e32 v58, 1.0, v84
	v_add_f32_e32 v77, 1.0, v77
	v_rcp_f32_e32 v58, v58
	v_rcp_f32_e32 v77, v77
	v_add_f32_e32 v54, v54, v85
	v_add_f32_e32 v56, v56, v85
	v_mul_f32_e32 v58, v58, v79
	v_mul_f32_e32 v59, v77, v76
	v_mul_f32_e32 v55, v58, v55
	v_lshlrev_b32_e32 v58, 16, v91
	v_and_b32_e32 v76, 0xffff0000, v91
	v_mul_f32_e32 v54, v59, v54
	v_mul_f32_e32 v59, v58, v58
	v_mul_f32_e32 v77, v76, v76
	v_fmamk_f32 v59, v59, 0xbdd2d3e7, v129
	v_fmamk_f32 v77, v77, 0xbdd2d3e7, v129
	v_mul_f32_e32 v59, v59, v58
	v_mul_f32_e32 v77, v77, v76
	v_exp_f32_e32 v59, v59
	v_exp_f32_e32 v77, v77
	v_cvt_pk_bf16_f32 v54, v54, v55
	v_add_f32_e32 v57, v57, v85
	v_add_f32_e32 v59, 1.0, v59
	v_add_f32_e32 v55, 1.0, v77
	v_rcp_f32_e32 v59, v59
	v_rcp_f32_e32 v55, v55
	v_add_f32_e32 v51, v51, v85
	v_add_f32_e32 v50, v50, v85
	v_mul_f32_e32 v58, v59, v58
	v_mul_f32_e32 v55, v55, v76
	v_mul_f32_e32 v56, v58, v56
	v_mul_f32_e32 v55, v55, v57
	s_waitcnt vmcnt(3)
	v_and_b32_e32 v58, 0xffff0000, v92
	v_cvt_pk_bf16_f32 v55, v56, v55
	v_lshlrev_b32_e32 v56, 16, v92
	v_mul_f32_e32 v59, v58, v58
	v_mul_f32_e32 v57, v56, v56
	v_fmamk_f32 v59, v59, 0xbdd2d3e7, v129
	v_fmamk_f32 v57, v57, 0xbdd2d3e7, v129
	v_mul_f32_e32 v59, v59, v58
	v_mul_f32_e32 v57, v57, v56
	v_exp_f32_e32 v59, v59
	v_exp_f32_e32 v57, v57
	global_store_dwordx2 v[60:61], v[54:55], off offset:32
	v_add_f32_e32 v52, v52, v85
	v_add_f32_e32 v54, 1.0, v59
	v_add_f32_e32 v57, 1.0, v57
	v_rcp_f32_e32 v54, v54
	v_rcp_f32_e32 v57, v57
	v_add_f32_e32 v53, v53, v85
	v_mfma_f32_16x16x32_bf16 v[34:37], v[18:21], v[86:89], v[34:37]
	v_mul_f32_e32 v54, v54, v58
	v_mul_f32_e32 v55, v57, v56
	v_mul_f32_e32 v51, v54, v51
	v_lshlrev_b32_e32 v54, 16, v93
	v_and_b32_e32 v56, 0xffff0000, v93
	v_mul_f32_e32 v50, v55, v50
	v_mul_f32_e32 v55, v54, v54
	v_mul_f32_e32 v57, v56, v56
	v_fmamk_f32 v55, v55, 0xbdd2d3e7, v129
	v_fmamk_f32 v57, v57, 0xbdd2d3e7, v129
	v_mul_f32_e32 v55, v55, v54
	v_mul_f32_e32 v57, v57, v56
	v_exp_f32_e32 v55, v55
	v_exp_f32_e32 v57, v57
	v_cvt_pk_bf16_f32 v50, v50, v51
	v_mfma_f32_16x16x32_bf16 v[46:49], v[22:25], v[86:89], v[46:49]
	v_add_f32_e32 v55, 1.0, v55
	v_add_f32_e32 v51, 1.0, v57
	v_rcp_f32_e32 v55, v55
	v_rcp_f32_e32 v51, v51
	v_mfma_f32_16x16x32_bf16 v[42:45], v[14:17], v[86:89], v[42:45]
	v_or_b32_e32 v57, 48, v82
	v_mul_f32_e32 v54, v55, v54
	v_mul_f32_e32 v51, v51, v56
	v_mul_f32_e32 v52, v54, v52
	v_mul_f32_e32 v51, v51, v53
	v_cvt_pk_bf16_f32 v51, v52, v51
	s_waitcnt vmcnt(3)
	v_lshlrev_b32_e32 v52, 16, v94
	v_mul_f32_e32 v53, v52, v52
	v_and_b32_e32 v54, 0xffff0000, v94
	v_fmamk_f32 v53, v53, 0xbdd2d3e7, v129
	v_mul_f32_e32 v55, v54, v54
	v_mul_f32_e32 v53, v53, v52
	v_fmamk_f32 v55, v55, 0xbdd2d3e7, v129
	v_mul_f32_e32 v55, v55, v54
	v_exp_f32_e32 v53, v53
	v_exp_f32_e32 v55, v55
	global_store_dwordx2 v[60:61], v[50:51], off offset:64
	v_add_f32_e32 v53, 1.0, v53
	v_rcp_f32_e32 v53, v53
	v_add_f32_e32 v50, 1.0, v55
	v_rcp_f32_e32 v50, v50
	v_mul_f32_e32 v51, v53, v52
	v_add_f32_e32 v52, v62, v85
	v_mul_f32_e32 v51, v51, v52
	v_mul_f32_e32 v50, v50, v54
	v_add_f32_e32 v52, v63, v85
	v_mul_f32_e32 v50, v50, v52
	v_lshlrev_b32_e32 v52, 16, v95
	v_mul_f32_e32 v53, v52, v52
	v_and_b32_e32 v54, 0xffff0000, v95
	v_fmamk_f32 v53, v53, 0xbdd2d3e7, v129
	v_mul_f32_e32 v55, v54, v54
	v_mul_f32_e32 v53, v53, v52
	v_fmamk_f32 v55, v55, 0xbdd2d3e7, v129
	v_mul_f32_e32 v55, v55, v54
	v_exp_f32_e32 v53, v53
	v_exp_f32_e32 v55, v55
	v_cvt_pk_bf16_f32 v50, v51, v50
	v_add_f32_e32 v53, 1.0, v53
	v_rcp_f32_e32 v53, v53
	v_add_f32_e32 v51, 1.0, v55
	v_rcp_f32_e32 v51, v51
	v_mul_f32_e32 v52, v53, v52
	v_add_f32_e32 v53, v64, v85
	v_mul_f32_e32 v52, v52, v53
	v_mul_f32_e32 v51, v51, v54
	v_add_f32_e32 v53, v65, v85
	v_mul_f32_e32 v51, v51, v53
	v_cvt_pk_bf16_f32 v51, v52, v51
	global_store_dwordx2 v[60:61], v[50:51], off offset:96
	global_load_dword v56, v81, s[12:13] offset:128
	global_load_dwordx2 v[54:55], v[68:69], off offset:32
	ds_read_b128 v[50:53], v83 offset:13248
	global_load_dwordx2 v[58:59], v[68:69], off offset:64
	global_load_dwordx2 v[60:61], v[68:69], off offset:96
	s_waitcnt vmcnt(8)
	v_lshlrev_b32_e32 v62, 16, v66
	s_waitcnt lgkmcnt(0)
	v_mfma_f32_16x16x32_bf16 v[26:29], v[30:33], v[50:53], v[26:29]
	v_mul_f32_e32 v30, v62, v62
	v_and_b32_e32 v63, 0xffff0000, v66
	v_fmamk_f32 v30, v30, 0xbdd2d3e7, v129
	v_mul_f32_e32 v31, v63, v63
	v_mul_f32_e32 v30, v30, v62
	v_fmamk_f32 v31, v31, 0xbdd2d3e7, v129
	v_mul_f32_e32 v31, v31, v63
	v_exp_f32_e32 v30, v30
	v_exp_f32_e32 v64, v31
	v_mad_u64_u32 v[32:33], s[0:1], v57, s3, v[74:75]
	v_add_f32_e32 v30, 1.0, v30
	v_rcp_f32_e32 v65, v30
	v_add_f32_e32 v64, 1.0, v64
	v_rcp_f32_e32 v64, v64
	global_load_dwordx2 v[30:31], v[32:33], off
	v_mul_f32_e32 v62, v65, v62
	v_mfma_f32_16x16x32_bf16 v[6:9], v[18:21], v[50:53], v[6:9]
	global_load_dwordx2 v[18:19], v[32:33], off offset:32
	s_waitcnt vmcnt(5)
	v_add_f32_e32 v38, v38, v56
	v_mul_f32_e32 v38, v62, v38
	v_mul_f32_e32 v62, v64, v63
	v_add_f32_e32 v39, v39, v56
	v_mul_f32_e32 v39, v62, v39
	v_lshlrev_b32_e32 v62, 16, v67
	v_mul_f32_e32 v63, v62, v62
	v_fmamk_f32 v63, v63, 0xbdd2d3e7, v129
	v_and_b32_e32 v64, 0xffff0000, v67
	v_mul_f32_e32 v63, v63, v62
	v_mul_f32_e32 v65, v64, v64
	v_fmamk_f32 v65, v65, 0xbdd2d3e7, v129
	v_mul_f32_e32 v65, v65, v64
	v_exp_f32_e32 v63, v63
	v_exp_f32_e32 v65, v65
	v_add_f32_e32 v63, 1.0, v63
	v_rcp_f32_e32 v63, v63
	v_cvt_pk_bf16_f32 v38, v38, v39
	v_add_f32_e32 v39, 1.0, v65
	v_rcp_f32_e32 v39, v39
	v_mul_f32_e32 v62, v63, v62
	v_add_f32_e32 v40, v40, v56
	v_mul_f32_e32 v40, v62, v40
	s_waitcnt vmcnt(4)
	v_lshlrev_b32_e32 v62, 16, v54
	v_and_b32_e32 v54, 0xffff0000, v54
	v_mul_f32_e32 v39, v39, v64
	v_mul_f32_e32 v64, v54, v54
	v_mul_f32_e32 v63, v62, v62
	v_fmamk_f32 v64, v64, 0xbdd2d3e7, v129
	v_fmamk_f32 v63, v63, 0xbdd2d3e7, v129
	v_mul_f32_e32 v64, v64, v54
	v_add_f32_e32 v41, v41, v56
	v_mul_f32_e32 v63, v63, v62
	v_mul_f32_e32 v39, v39, v41
	v_cvt_pk_bf16_f32 v39, v40, v39
	v_mad_u64_u32 v[40:41], s[0:1], v78, s3, v[72:73]
	v_exp_f32_e32 v64, v64
	v_lshl_add_u64 v[40:41], v[40:41], 0, s[8:9]
	v_exp_f32_e32 v63, v63
	v_lshl_add_u64 v[40:41], v[40:41], 0, v[0:1]
	v_lshl_add_u64 v[40:41], v[40:41], 0, v[70:71]
	global_store_dwordx2 v[40:41], v[38:39], off
	v_add_f32_e32 v38, 1.0, v64
	v_add_f32_e32 v63, 1.0, v63
	v_rcp_f32_e32 v38, v38
	v_rcp_f32_e32 v63, v63
	v_add_f32_e32 v35, v35, v56
	v_add_f32_e32 v34, v34, v56
	v_mul_f32_e32 v38, v38, v54
	v_mul_f32_e32 v39, v63, v62
	v_mul_f32_e32 v35, v38, v35
	v_lshlrev_b32_e32 v38, 16, v55
	v_and_b32_e32 v54, 0xffff0000, v55
	v_mul_f32_e32 v34, v39, v34
	v_mul_f32_e32 v39, v38, v38
	v_mul_f32_e32 v55, v54, v54
	v_fmamk_f32 v39, v39, 0xbdd2d3e7, v129
	v_fmamk_f32 v55, v55, 0xbdd2d3e7, v129
	v_mul_f32_e32 v39, v39, v38
	v_mul_f32_e32 v55, v55, v54
	v_exp_f32_e32 v39, v39
	v_exp_f32_e32 v55, v55
	v_cvt_pk_bf16_f32 v34, v34, v35
	v_add_f32_e32 v36, v36, v56
	v_add_f32_e32 v39, 1.0, v39
	v_add_f32_e32 v35, 1.0, v55
	v_rcp_f32_e32 v39, v39
	v_rcp_f32_e32 v35, v35
	v_add_f32_e32 v37, v37, v56
	v_mfma_f32_16x16x32_bf16 v[2:5], v[22:25], v[50:53], v[2:5]
	v_mul_f32_e32 v38, v39, v38
	v_mul_f32_e32 v35, v35, v54
	v_mul_f32_e32 v36, v38, v36
	v_mul_f32_e32 v35, v35, v37
	v_cvt_pk_bf16_f32 v35, v36, v35
	s_waitcnt vmcnt(4)
	v_lshlrev_b32_e32 v36, 16, v58
	v_mul_f32_e32 v37, v36, v36
	v_and_b32_e32 v38, 0xffff0000, v58
	v_fmamk_f32 v37, v37, 0xbdd2d3e7, v129
	v_mul_f32_e32 v39, v38, v38
	v_mul_f32_e32 v37, v37, v36
	v_fmamk_f32 v39, v39, 0xbdd2d3e7, v129
	v_mul_f32_e32 v39, v39, v38
	v_exp_f32_e32 v37, v37
	v_exp_f32_e32 v39, v39
	global_store_dwordx2 v[40:41], v[34:35], off offset:32
	v_add_f32_e32 v37, 1.0, v37
	v_rcp_f32_e32 v37, v37
	v_add_f32_e32 v34, 1.0, v39
	v_rcp_f32_e32 v34, v34
	s_waitcnt vmcnt(3)
	v_lshlrev_b32_e32 v24, 16, v30
	v_mul_f32_e32 v35, v37, v36
	v_add_f32_e32 v36, v46, v56
	v_mul_f32_e32 v35, v35, v36
	v_mul_f32_e32 v34, v34, v38
	v_add_f32_e32 v36, v47, v56
	v_mul_f32_e32 v34, v34, v36
	v_lshlrev_b32_e32 v36, 16, v59
	v_mul_f32_e32 v37, v36, v36
	v_and_b32_e32 v38, 0xffff0000, v59
	v_fmamk_f32 v37, v37, 0xbdd2d3e7, v129
	v_mul_f32_e32 v39, v38, v38
	v_mul_f32_e32 v37, v37, v36
	v_fmamk_f32 v39, v39, 0xbdd2d3e7, v129
	v_mul_f32_e32 v39, v39, v38
	v_exp_f32_e32 v37, v37
	v_exp_f32_e32 v39, v39
	v_cvt_pk_bf16_f32 v34, v35, v34
	v_add_f32_e32 v37, 1.0, v37
	v_rcp_f32_e32 v37, v37
	v_add_f32_e32 v35, 1.0, v39
	v_rcp_f32_e32 v35, v35
	v_mul_f32_e32 v25, 0x3d372713, v24
	v_mul_f32_e32 v36, v37, v36
	v_add_f32_e32 v37, v48, v56
	v_mul_f32_e32 v36, v36, v37
	v_mul_f32_e32 v35, v35, v38
	v_add_f32_e32 v37, v49, v56
	v_mul_f32_e32 v35, v35, v37
	v_cvt_pk_bf16_f32 v35, v36, v35
	v_lshlrev_b32_e32 v36, 16, v60
	v_mul_f32_e32 v37, v36, v36
	v_and_b32_e32 v38, 0xffff0000, v60
	v_fmamk_f32 v37, v37, 0xbdd2d3e7, v129
	v_mul_f32_e32 v39, v38, v38
	v_mul_f32_e32 v37, v37, v36
	v_fmamk_f32 v39, v39, 0xbdd2d3e7, v129
	v_mul_f32_e32 v39, v39, v38
	v_exp_f32_e32 v37, v37
	v_exp_f32_e32 v39, v39
	global_store_dwordx2 v[40:41], v[34:35], off offset:64
	v_add_f32_e32 v37, 1.0, v37
	v_rcp_f32_e32 v37, v37
	v_add_f32_e32 v34, 1.0, v39
	v_rcp_f32_e32 v34, v34
	v_and_b32_e32 v30, 0xffff0000, v30
	v_mul_f32_e32 v35, v37, v36
	v_add_f32_e32 v36, v42, v56
	v_mul_f32_e32 v35, v35, v36
	v_mul_f32_e32 v34, v34, v38
	v_add_f32_e32 v36, v43, v56
	v_mul_f32_e32 v34, v34, v36
	v_lshlrev_b32_e32 v36, 16, v61
	v_mul_f32_e32 v37, v36, v36
	v_and_b32_e32 v38, 0xffff0000, v61
	v_fmamk_f32 v37, v37, 0xbdd2d3e7, v129
	v_mul_f32_e32 v39, v38, v38
	v_mul_f32_e32 v37, v37, v36
	v_fmamk_f32 v39, v39, 0xbdd2d3e7, v129
	v_mul_f32_e32 v39, v39, v38
	v_exp_f32_e32 v37, v37
	v_exp_f32_e32 v39, v39
	v_cvt_pk_bf16_f32 v34, v35, v34
	v_add_f32_e32 v37, 1.0, v37
	v_rcp_f32_e32 v37, v37
	v_add_f32_e32 v35, 1.0, v39
	v_rcp_f32_e32 v35, v35
	v_mul_f32_e32 v25, v25, v24
	v_mul_f32_e32 v36, v37, v36
	v_add_f32_e32 v37, v44, v56
	v_mul_f32_e32 v36, v36, v37
	v_mul_f32_e32 v35, v35, v38
	v_add_f32_e32 v37, v45, v56
	v_mul_f32_e32 v35, v35, v37
	v_cvt_pk_bf16_f32 v35, v36, v35
	global_store_dwordx2 v[40:41], v[34:35], off offset:96
	global_load_dword v34, v81, s[12:13] offset:192
	s_nop 0
	global_load_dwordx2 v[20:21], v[32:33], off offset:64
	global_load_dwordx2 v[22:23], v[32:33], off offset:96
	v_mul_f32_e32 v32, v30, v30
	v_fma_f32 v25, v25, v24, v24
	v_fmamk_f32 v32, v32, 0xbdd2d3e7, v129
	v_mul_f32_e32 v25, 0xbfcc422a, v25
	v_mul_f32_e32 v32, v32, v30
	v_mul_f32_e32 v25, 0x3fb8aa3b, v25
	v_exp_f32_e32 v25, v25
	v_exp_f32_e32 v32, v32
	v_mfma_f32_16x16x32_bf16 v[10:13], v[14:17], v[50:53], v[10:13]
	v_add_f32_e32 v25, 1.0, v25
	v_rcp_f32_e32 v25, v25
	v_add_f32_e32 v14, 1.0, v32
	v_rcp_f32_e32 v14, v14
	v_mul_f32_e32 v15, v25, v24
	v_and_b32_e32 v24, 0xffff0000, v31
	v_mul_f32_e32 v14, v14, v30
	v_mul_f32_e32 v25, v24, v24
	v_fmamk_f32 v25, v25, 0xbdd2d3e7, v129
	v_mul_f32_e32 v25, v25, v24
	v_exp_f32_e32 v25, v25
	s_waitcnt vmcnt(2)
	v_add_f32_e32 v16, v26, v34
	v_mul_f32_e32 v15, v15, v16
	v_add_f32_e32 v16, v27, v34
	v_mul_f32_e32 v14, v14, v16
	v_lshlrev_b32_e32 v16, 16, v31
	v_mul_f32_e32 v17, v16, v16
	v_fmamk_f32 v17, v17, 0xbdd2d3e7, v129
	v_mul_f32_e32 v17, v17, v16
	v_exp_f32_e32 v17, v17
	v_cvt_pk_bf16_f32 v14, v15, v14
	v_add_f32_e32 v15, 1.0, v25
	v_rcp_f32_e32 v15, v15
	v_add_f32_e32 v17, 1.0, v17
	v_rcp_f32_e32 v17, v17
	v_add_f32_e32 v6, v6, v34
	v_mul_f32_e32 v15, v15, v24
	v_add_f32_e32 v7, v7, v34
	v_mul_f32_e32 v16, v17, v16
	v_add_f32_e32 v17, v28, v34
	v_mul_f32_e32 v16, v16, v17
	v_add_f32_e32 v17, v29, v34
	v_mul_f32_e32 v15, v15, v17
	v_cvt_pk_bf16_f32 v15, v16, v15
	v_mad_u64_u32 v[16:17], s[0:1], v57, s3, v[72:73]
	v_lshl_add_u64 v[16:17], v[16:17], 0, s[8:9]
	v_lshl_add_u64 v[16:17], v[16:17], 0, v[0:1]
	v_lshlrev_b32_e32 v0, 16, v18
	v_mul_f32_e32 v24, v0, v0
	v_and_b32_e32 v18, 0xffff0000, v18
	v_fmamk_f32 v24, v24, 0xbdd2d3e7, v129
	v_mul_f32_e32 v25, v18, v18
	v_mul_f32_e32 v24, v24, v0
	v_fmamk_f32 v25, v25, 0xbdd2d3e7, v129
	v_mul_f32_e32 v25, v25, v18
	v_exp_f32_e32 v24, v24
	v_exp_f32_e32 v25, v25
	v_lshl_add_u64 v[16:17], v[16:17], 0, v[70:71]
	v_add_f32_e32 v24, 1.0, v24
	v_rcp_f32_e32 v24, v24
	global_store_dwordx2 v[16:17], v[14:15], off
	v_add_f32_e32 v14, 1.0, v25
	v_rcp_f32_e32 v14, v14
	v_mul_f32_e32 v0, v24, v0
	v_mul_f32_e32 v0, v0, v6
	v_and_b32_e32 v15, 0xffff0000, v19
	v_mul_f32_e32 v6, v14, v18
	v_mul_f32_e32 v6, v6, v7
	v_lshlrev_b32_e32 v7, 16, v19
	v_mul_f32_e32 v14, v7, v7
	v_fmamk_f32 v14, v14, 0xbdd2d3e7, v129
	v_mul_f32_e32 v18, v15, v15
	v_mul_f32_e32 v14, v14, v7
	v_fmamk_f32 v18, v18, 0xbdd2d3e7, v129
	v_mul_f32_e32 v18, v18, v15
	v_exp_f32_e32 v14, v14
	v_exp_f32_e32 v18, v18
	v_cvt_pk_bf16_f32 v6, v0, v6
	v_add_f32_e32 v14, 1.0, v14
	v_rcp_f32_e32 v14, v14
	v_add_f32_e32 v0, 1.0, v18
	v_rcp_f32_e32 v0, v0
	v_add_f32_e32 v8, v8, v34
	v_mul_f32_e32 v7, v14, v7
	v_mul_f32_e32 v7, v7, v8
	v_mul_f32_e32 v0, v0, v15
	v_add_f32_e32 v8, v9, v34
	v_mul_f32_e32 v0, v0, v8
	v_cvt_pk_bf16_f32 v7, v7, v0
	s_waitcnt vmcnt(2)
	v_lshlrev_b32_e32 v0, 16, v20
	v_mul_f32_e32 v8, v0, v0
	v_and_b32_e32 v9, 0xffff0000, v20
	v_fmamk_f32 v8, v8, 0xbdd2d3e7, v129
	v_mul_f32_e32 v14, v9, v9
	v_mul_f32_e32 v8, v8, v0
	v_fmamk_f32 v14, v14, 0xbdd2d3e7, v129
	v_mul_f32_e32 v14, v14, v9
	v_exp_f32_e32 v8, v8
	v_exp_f32_e32 v14, v14
	global_store_dwordx2 v[16:17], v[6:7], off offset:32
	v_add_f32_e32 v8, 1.0, v8
	v_rcp_f32_e32 v8, v8
	v_add_f32_e32 v6, 1.0, v14
	v_rcp_f32_e32 v6, v6
	v_add_f32_e32 v2, v2, v34
	v_mul_f32_e32 v0, v8, v0
	v_mul_f32_e32 v0, v0, v2
	v_mul_f32_e32 v2, v6, v9
	v_add_f32_e32 v3, v3, v34
	v_mul_f32_e32 v2, v2, v3
	v_lshlrev_b32_e32 v3, 16, v21
	v_mul_f32_e32 v6, v3, v3
	v_and_b32_e32 v7, 0xffff0000, v21
	v_fmamk_f32 v6, v6, 0xbdd2d3e7, v129
	v_mul_f32_e32 v8, v7, v7
	v_mul_f32_e32 v6, v6, v3
	v_fmamk_f32 v8, v8, 0xbdd2d3e7, v129
	v_mul_f32_e32 v8, v8, v7
	v_exp_f32_e32 v6, v6
	v_exp_f32_e32 v8, v8
	v_cvt_pk_bf16_f32 v2, v0, v2
	v_add_f32_e32 v6, 1.0, v6
	v_rcp_f32_e32 v6, v6
	v_add_f32_e32 v0, 1.0, v8
	v_rcp_f32_e32 v0, v0
	v_add_f32_e32 v4, v4, v34
	v_mul_f32_e32 v3, v6, v3
	v_mul_f32_e32 v3, v3, v4
	v_mul_f32_e32 v0, v0, v7
	v_add_f32_e32 v4, v5, v34
	v_mul_f32_e32 v0, v0, v4
	v_cvt_pk_bf16_f32 v3, v3, v0
	s_waitcnt vmcnt(2)
	v_lshlrev_b32_e32 v0, 16, v22
	v_mul_f32_e32 v4, v0, v0
	v_and_b32_e32 v5, 0xffff0000, v22
	v_fmamk_f32 v4, v4, 0xbdd2d3e7, v129
	v_mul_f32_e32 v6, v5, v5
	v_mul_f32_e32 v4, v4, v0
	v_fmamk_f32 v6, v6, 0xbdd2d3e7, v129
	v_mul_f32_e32 v6, v6, v5
	v_exp_f32_e32 v4, v4
	v_exp_f32_e32 v6, v6
	global_store_dwordx2 v[16:17], v[2:3], off offset:64
	v_add_f32_e32 v4, 1.0, v4
	v_rcp_f32_e32 v4, v4
	v_add_f32_e32 v2, 1.0, v6
	v_rcp_f32_e32 v2, v2
	v_add_f32_e32 v3, v10, v34
	v_mul_f32_e32 v0, v4, v0
	v_mul_f32_e32 v0, v0, v3
	v_mul_f32_e32 v2, v2, v5
	v_add_f32_e32 v3, v11, v34
	v_mul_f32_e32 v2, v2, v3
	v_lshlrev_b32_e32 v3, 16, v23
	v_mul_f32_e32 v4, v3, v3
	v_and_b32_e32 v5, 0xffff0000, v23
	v_fmamk_f32 v4, v4, 0xbdd2d3e7, v129
	v_mul_f32_e32 v6, v5, v5
	v_mul_f32_e32 v4, v4, v3
	v_fmamk_f32 v6, v6, 0xbdd2d3e7, v129
	v_mul_f32_e32 v6, v6, v5
	v_exp_f32_e32 v4, v4
	v_exp_f32_e32 v6, v6
	v_cvt_pk_bf16_f32 v2, v0, v2
	v_add_f32_e32 v4, 1.0, v4
	v_rcp_f32_e32 v4, v4
	v_add_f32_e32 v0, 1.0, v6
	v_rcp_f32_e32 v0, v0
	v_mul_f32_e32 v3, v4, v3
	v_add_f32_e32 v4, v12, v34
	v_mul_f32_e32 v3, v3, v4
	v_mul_f32_e32 v0, v0, v5
	v_add_f32_e32 v4, v13, v34
	v_mul_f32_e32 v0, v0, v4
	v_cvt_pk_bf16_f32 v3, v3, v0
	global_store_dwordx2 v[16:17], v[2:3], off offset:96
	s_barrier
	s_cbranch_scc0 .LBB0_626
	s_mov_b32 s85, s10
	s_sub_i32 s10, s85, 0x80
	s_cmpk_lt_u32 s85, 0x180
	s_cbranch_scc1 .Lrk_entry
	s_sub_i32 s10, s85, 0x180
